# HGRN2 Q/K image row stride 144->136 and GDN K^T/V^T image row stride 80->72 elements (bank-conflict-free fragment reads)
# baseline (speedup 1.0000x reference)
; __device__ __forceinline__ int hg_row(int b, int d, int pos) {
;     return (pos < TCX) ? (b * TCX + (d ? (TCX - 1 - pos) : pos)) : (ROWS_C + b * TL + (d ? (TL - 1 - (pos - TCX)) : (pos - TCX)));
; }
; __device__ __forceinline__ void phase_hg2(Frame& F, int j, bool ctx_out, bool dry = false) {
;     FRAME_TID(F);
;     gb P = (gb)(F.ws + WS_P); gb OF = (gb)(F.ws + WS_O);
;     gcf lbl = F.in[I_HGLB]; gcf ng = F.in[I_HGNG] + j * 128;
;     LAS bf16* Qt = (LAS bf16*)(F.lds + HG_QT); LAS bf16* Kt = (LAS bf16*)(F.lds + HG_KT); LAS bf16* KtT = (LAS bf16*)(F.lds + HG_KTT); LAS bf16* VT = (LAS bf16*)(F.lds + HG_VT);
;     LAS bf16* ATT = (LAS bf16*)(F.lds + HG_ATT); LAS bf16* SB = (LAS bf16*)(F.lds + HG_SB);
;     LAS float* er = (LAS float*)(F.lds + HG_ER); LAS float* eend = (LAS float*)(F.lds + HG_EEND); LAS float* segs = (LAS float*)(F.lds + HG_SEG);
;     LAS float* s_ng = (LAS float*)(F.lds + 131072);
;     LAS float* O32 = (LAS float*)(F.lds + HG_QT);
;     const int c2_ = F.tid & 63, seg_ = F.tid >> 6;
;     const int l15_ = F.lane & 15, q4_ = F.lane >> 4, vb = F.wave;
;     const int rt = F.tid >> 3, g8 = F.tid & 7;
;     for (int item = blockIdx.x; item < NB * 16; item += F.G) {
;         const int b = item >> 4, h = item & 15;
;         if (F.tid < 128) s_ng[F.tid] = ng[F.tid];
;         for (int d = 0; d < 2; ++d) {
;             float lb0, lb1;
;             { const int cc = 2 * c2_;
;               const float a0 = lbl[(0 * 2 + d) * DM + h * 128 + cc], a1 = lbl[(1 * 2 + d) * DM + h * 128 + cc], b0 = lbl[(0 * 2 + d) * DM + h * 128 + cc + 1], b1 = lbl[(1 * 2 + d) * DM + h * 128 + cc + 1];
;               const float mx = fmaxf(a0, a1), e0 = __expf(a0 - mx), e1 = __expf(a1 - mx), my = fmaxf(b0, b1), f0 = __expf(b0 - my), f1 = __expf(b1 - my);
;               lb0 = (j == 0) ? 0.f : e1 / (e0 + e1); lb1 = (j == 0) ? 0.f : f1 / (f0 + f1); }
;             f32x4 S[8];
; #pragma unroll
;             for (int kt = 0; kt < 8; ++kt) S[kt] = (f32x4){0.f, 0.f, 0.f, 0.f};
;             unsigned rq[8], rf[8], rv[8];
;             {
;                 gcb pr = P + h * 128 + 2 * c2_;
; #pragma unroll
;                 for (int i = 0; i < 8; ++i) { const size_t ro = (size_t)hg_row(b, d, seg_ * 8 + i) * HG_N; rq[i] = *(GAS const unsigned*)(pr + ro); rv[i] = *(GAS const unsigned*)(pr + ro + DM); rf[i] = *(GAS const unsigned*)(pr + ro + (2 + d) * DM); }
;             }
.LBB0_246:
	s_cmp_gt_i32 s52, 3
	v_writelane_b32 v255, s69, 0
	s_cselect_b64 s[0:1], -1, 0
	s_cmp_lt_i32 s53, 4
	v_writelane_b32 v255, s72, 1
	s_cselect_b64 s[2:3], -1, 0
	v_writelane_b32 v255, s73, 2
	s_or_b64 s[0:1], s[0:1], s[2:3]
	v_writelane_b32 v254, s70, 62
	v_writelane_b32 v255, s94, 3
	s_and_b64 vcc, exec, s[0:1]
	v_writelane_b32 v254, s71, 63
	v_writelane_b32 v255, s95, 4
	s_cbranch_vccnz .LBB0_341
	s_cmpk_gt_i32 s73, 0xff
	v_mbcnt_lo_u32_b32 v0, -1, 0
	v_mbcnt_hi_u32_b32 v0, -1, v0
	s_cbranch_scc1 .LBB0_291
	v_readlane_b32 s0, v255, 3
	v_readlane_b32 s1, v255, 4
	s_load_dwordx2 s[2:3], s[0:1], 0xd8
	v_readlane_b32 s5, v254, 57
	v_readlane_b32 s4, v254, 0
	v_and_b32_e32 v122, 63, v0
	v_readlane_b32 s36, v254, 21
	s_waitcnt lgkmcnt(0)
	s_add_u32 s0, s2, 0xa700000
	v_writelane_b32 v255, s0, 5
	s_addc_u32 s0, s3, 0
	v_writelane_b32 v255, s0, 7
	s_add_u32 s0, s2, 0x41900000
	v_writelane_b32 v255, s0, 8
	s_addc_u32 s0, s3, 0
	s_cmpk_lt_u32 s5, 0x100
	s_cselect_b64 s[70:71], -1, 0
	s_lshl_b32 s1, s33, 9
	s_add_i32 s10, s1, 0
	s_lshl_b32 s12, s33, 4
	v_add_u32_e32 v2, s4, v0
	s_add_i32 s10, s10, 0x1ec00
	s_lshl_b32 s11, s33, 3
	s_add_i32 s13, s12, 0
	v_writelane_b32 v255, s0, 10
	v_ashrrev_i32_e32 v125, 3, v2
	s_add_u32 s1, s2, 0xa704000
	v_and_b32_e32 v127, -8, v125
	s_movk_i32 s0, 0x100
	v_writelane_b32 v255, s1, 11
	s_addc_u32 s1, s3, 0
	v_writelane_b32 v255, s1, 12
	v_cmp_gt_i32_e64 s[6:7], s0, v127
	v_or_b32_e32 v131, 1, v127
	v_or_b32_e32 v135, 2, v127
	v_writelane_b32 v255, s6, 13
	v_or_b32_e32 v139, 3, v127
	v_or_b32_e32 v143, 4, v127
	v_writelane_b32 v255, s7, 14
	v_cmp_gt_i32_e64 s[6:7], s0, v131
	v_or_b32_e32 v147, 5, v127
	s_cmp_lt_u32 s5, 64
	v_writelane_b32 v255, s6, 15
	v_or_b32_e32 v151, 6, v127
	s_cselect_b64 s[2:3], -1, 0
	v_writelane_b32 v255, s7, 16
	v_cmp_gt_i32_e64 s[6:7], s0, v135
	s_add_i32 s14, s4, 0
	v_or_b32_e32 v155, 7, v125
	v_writelane_b32 v255, s6, 17
	s_cmpk_lt_u32 s5, 0x80
	s_cselect_b64 s[20:21], -1, 0
	v_writelane_b32 v255, s7, 18
	v_cmp_gt_i32_e64 s[6:7], s0, v139
	s_cmpk_lt_u32 s5, 0xc0
	s_cselect_b64 s[22:23], -1, 0
	v_writelane_b32 v255, s6, 19
	s_cmpk_gt_u32 s5, 0x13f
	s_cselect_b64 s[24:25], -1, 0
	v_writelane_b32 v255, s7, 20
	v_cmp_gt_i32_e64 s[6:7], s0, v143
	s_cmpk_gt_u32 s5, 0x17f
	s_cselect_b64 s[26:27], -1, 0
	v_writelane_b32 v255, s6, 21
	s_cmpk_gt_u32 s5, 0x1bf
	s_cselect_b64 s[28:29], -1, 0
	v_writelane_b32 v255, s7, 22
	v_cmp_gt_i32_e64 s[6:7], s0, v147
	s_cmpk_gt_u32 s5, 0x1ff
	s_cselect_b64 s[30:31], -1, 0
	v_writelane_b32 v255, s6, 23
	v_and_b32_e32 v123, 15, v0
	v_ashrrev_i32_e32 v124, 4, v0
	v_writelane_b32 v255, s7, 24
	v_cmp_gt_i32_e64 s[6:7], s0, v151
	v_cmp_gt_i32_e64 s[0:1], s0, v155
	v_and_b32_e32 v126, 7, v0
	v_writelane_b32 v255, s6, 25
	v_lshlrev_b32_e32 v0, 1, v122
	v_mov_b32_e32 v101, 0
	v_writelane_b32 v255, s7, 26
	v_writelane_b32 v255, s0, 27
	v_ashrrev_i32_e32 v3, 31, v2
	v_readlane_b32 s40, v254, 25
	v_writelane_b32 v255, s1, 28
	s_movk_i32 s0, 0x80
	v_cmp_gt_i32_e64 s[0:1], s0, v2
	v_readlane_b32 s41, v254, 26
	s_mov_b32 s73, 0
	v_writelane_b32 v255, s0, 29
	v_sub_u32_e32 v128, 0x8ff, v127
	v_add_u32_e32 v129, 0xffffff00, v127
	v_writelane_b32 v255, s1, 30
	s_add_i32 s0, 0, 0x20000
	v_lshl_add_u32 v159, v2, 2, s0
	s_lshl_b32 s0, s33, 1
	s_lshr_b32 s1, s5, 7
	s_and_b32 s0, s0, 2
	s_cmp_ge_u32 s0, s1
	s_cselect_b64 s[74:75], -1, 0
	s_lshl_b32 s15, s1, 4
	s_lshl_b32 s16, s0, 4
	s_or_b32 s0, s0, 1
	s_cmp_ge_u32 s0, s1
	s_cselect_b64 s[92:93], -1, 0
	s_lshl_b32 s17, s0, 4
	s_mul_i32 s0, s33, 0x880
	s_add_i32 s18, s0, 0
	v_readlane_b32 s0, v255, 2
	v_sub_u32_e32 v130, 0xff, v127
	v_sub_u32_e32 v132, 0x8ff, v131
	v_add_u32_e32 v133, 0xffffff01, v127
	v_sub_u32_e32 v134, 0xff, v131
	v_sub_u32_e32 v136, 0x8ff, v135
	v_add_u32_e32 v137, 0xffffff02, v127
	v_sub_u32_e32 v138, 0xff, v135
	v_sub_u32_e32 v140, 0x8ff, v139
	v_add_u32_e32 v141, 0xffffff03, v127
	v_sub_u32_e32 v142, 0xff, v139
	v_sub_u32_e32 v144, 0x8ff, v143
	v_add_u32_e32 v145, 0xffffff04, v127
	v_sub_u32_e32 v146, 0xff, v143
	v_sub_u32_e32 v148, 0x8ff, v147
	v_add_u32_e32 v149, 0xffffff05, v127
	v_sub_u32_e32 v150, 0xff, v147
	v_sub_u32_e32 v152, 0x8ff, v151
	v_add_u32_e32 v153, 0xffffff06, v127
	v_sub_u32_e32 v154, 0xff, v151
	v_sub_u32_e32 v156, 0x8ff, v155
	v_add_u32_e32 v157, 0xffffff00, v155
	v_sub_u32_e32 v158, 0xff, v155
	v_lshl_add_u64 v[102:103], v[2:3], 2, s[40:41]
	v_lshlrev_b32_e32 v104, 1, v0
	v_mov_b32_e32 v105, v101
	s_movk_i32 s19, 0x5000
	s_movk_i32 s76, 0x1000
	s_mov_b32 s77, 0xffff0000
	s_mov_b32 s78, 0xbfb8aa3b
	s_mov_b32 s79, 0xffff
	s_movk_i32 s80, 0x2800
	s_movk_i32 s81, 0x110
	s_movk_i32 s82, 0xa0
	s_add_i32 s83, 0, 0x13000
	v_mov_b32_e32 v160, 0x358637bd
	s_mov_b32 s6, s0
	v_readlane_b32 s37, v254, 22
	v_readlane_b32 s38, v254, 23
	v_readlane_b32 s39, v254, 24
	v_readlane_b32 s42, v254, 27
	v_readlane_b32 s43, v254, 28
	v_readlane_b32 s44, v254, 29
	v_readlane_b32 s45, v254, 30
	v_readlane_b32 s46, v254, 31
	v_readlane_b32 s47, v254, 32
	v_readlane_b32 s48, v254, 33
	v_readlane_b32 s49, v254, 34
	v_readlane_b32 s50, v254, 35
	v_readlane_b32 s51, v254, 36
	s_branch .LBB0_250

; #define LAS __attribute__((address_space(3)))
; __device__ __forceinline__ void phase_hg2(Frame& F, int j, bool ctx_out, bool dry = false) {
;     ...
;                 float m0 = 1.f, m1 = 1.f, er0 = 1.f, er1 = 1.f, en0 = 1.f, en1 = 1.f;
; #pragma unroll
;                 for (int sg = 0; sg < 8; ++sg) { const v2f g = *(const LAS v2f*)(segs + sg * 128 + 2 * c2);
;                     if (sg < 4) { er0 = fmaxf(er0 * g.x, 1e-30f); er1 = fmaxf(er1 * g.y, 1e-30f); } else { en0 = fmaxf(en0 * g.x, 1e-30f); en1 = fmaxf(en1 * g.y, 1e-30f); }
;                     const bool inm = (seg >= 4) ? (sg >= 4 && sg < seg) : (sg > seg && sg < 4);
;                     if (inm) { m0 = fmaxf(m0 * g.x, 1e-30f); m1 = fmaxf(m1 * g.y, 1e-30f); } }
;                 if (seg == 0) { *(LAS v2f*)(er + 2 * c2) = (v2f){er0, er1}; *(LAS v2f*)(eend + 2 * c2) = (v2f){en0, en1}; }
;                 {
;                     unsigned k0[8], k1[8];
;                     const v2f m2 = (v2f){m0, m1};
;     ...
;                     if (seg >= 4) { HG_PASS2(small_, big_) } else { HG_PASS2(big_, small_) }
;     ...
;                     *(LAS v4u*)(KtT + (2 * c2) * HTS + seg * 8) = (v4u){k0[0] | (k0[1] << 16), k0[2] | (k0[3] << 16), k0[4] | (k0[5] << 16), k0[6] | (k0[7] << 16)};
;                     *(LAS v4u*)(KtT + (2 * c2 + 1) * HTS + seg * 8) = (v4u){k1[0] | (k1[1] << 16), k1[2] | (k1[3] << 16), k1[4] | (k1[5] << 16), k1[6] | (k1[7] << 16)};
;                 }
.LBB0_271:
	s_waitcnt lgkmcnt(3)
	v_max_f32_e32 v24, v24, v24
	v_max_f32_e32 v25, v25, v25
	v_max_f32_e32 v24, 0xda24260, v24
	v_max_f32_e32 v25, 0xda24260, v25
	v_cndmask_b32_e64 v25, 1.0, v25, s[2:3]
	v_cndmask_b32_e64 v24, 1.0, v24, s[2:3]
	v_mul_f32_e32 v24, v26, v24
	v_mul_f32_e32 v25, v27, v25
	v_max_f32_e32 v24, 0xda24260, v24
	v_max_f32_e32 v25, 0xda24260, v25
	v_cndmask_b32_e64 v25, 1.0, v25, s[20:21]
	v_cndmask_b32_e64 v24, 1.0, v24, s[20:21]
	s_waitcnt lgkmcnt(2)
	v_mul_f32_e32 v20, v20, v24
	v_mul_f32_e32 v21, v21, v25
	v_max_f32_e32 v20, 0xda24260, v20
	v_max_f32_e32 v21, 0xda24260, v21
	v_cndmask_b32_e64 v21, 1.0, v21, s[22:23]
	v_cndmask_b32_e64 v20, 1.0, v20, s[22:23]
	v_mul_f32_e32 v22, v22, v20
	v_mul_f32_e32 v23, v23, v21
	v_max_f32_e32 v22, 0xda24260, v22
	v_max_f32_e32 v23, 0xda24260, v23
	v_cndmask_b32_e64 v21, v21, v23, s[24:25]
	v_cndmask_b32_e64 v20, v20, v22, s[24:25]
	s_waitcnt lgkmcnt(1)
	v_mul_f32_e32 v16, v16, v20
	v_mul_f32_e32 v17, v17, v21
	v_max_f32_e32 v16, 0xda24260, v16
	v_max_f32_e32 v17, 0xda24260, v17
	v_cndmask_b32_e64 v17, v21, v17, s[26:27]
	v_cndmask_b32_e64 v16, v20, v16, s[26:27]
	v_mul_f32_e32 v18, v18, v16
	v_mul_f32_e32 v19, v19, v17
	v_max_f32_e32 v18, 0xda24260, v18
	v_max_f32_e32 v19, 0xda24260, v19
	v_cndmask_b32_e64 v17, v17, v19, s[28:29]
	v_cndmask_b32_e64 v16, v16, v18, s[28:29]
	s_waitcnt lgkmcnt(0)
	v_mul_f32_e32 v18, v116, v16
	v_mul_f32_e32 v19, v117, v17
	v_max_f32_e32 v18, 0xda24260, v18
	v_max_f32_e32 v19, 0xda24260, v19
	v_cndmask_b32_e64 v17, v17, v19, s[30:31]
	v_cndmask_b32_e64 v16, v16, v18, s[30:31]
	v_cndmask_b32_e64 v18, v41, v43, s[42:43]
	v_cndmask_b32_e64 v19, v40, v42, s[40:41]
	v_cvt_pk_bf16_f32 v20, v19, v18
	v_cndmask_b32_e64 v18, v47, v49, s[46:47]
	v_cndmask_b32_e64 v19, v46, v48, s[44:45]
	v_cvt_pk_bf16_f32 v21, v19, v18
	v_cndmask_b32_e64 v18, v51, v85, s[50:51]
	v_cndmask_b32_e64 v19, v50, v84, s[48:49]
	v_cvt_pk_bf16_f32 v46, v19, v18
	v_cndmask_b32_e64 v18, v87, v89, s[54:55]
	v_cndmask_b32_e64 v19, v86, v88, s[52:53]
	v_cvt_pk_bf16_f32 v47, v19, v18
	v_cndmask_b32_e64 v18, v91, v93, s[58:59]
	v_cndmask_b32_e64 v19, v90, v92, s[56:57]
	v_cvt_pk_bf16_f32 v50, v19, v18
	v_cndmask_b32_e64 v18, v95, v97, s[64:65]
	v_cndmask_b32_e64 v19, v94, v96, s[62:63]
	v_cvt_pk_bf16_f32 v116, v19, v18
	v_cndmask_b32_e64 v18, v99, v109, s[68:69]
	v_cndmask_b32_e64 v19, v98, v108, s[66:67]
	v_cvt_pk_bf16_f32 v117, v19, v18
	v_pk_mul_f32 v[18:19], v[44:45], v[16:17]
	v_lshl_add_u32 v198, v195, 1, s18
	v_max_f32_e32 v22, 0xda24260, v18
	v_max_f32_e32 v23, 0xda24260, v19
	v_pk_mul_f32 v[18:19], v[114:115], v[16:17]
	v_rcp_f32_e32 v24, v22
	v_max_f32_e32 v42, 0xda24260, v18
	v_max_f32_e32 v43, 0xda24260, v19
	v_pk_mul_f32 v[18:19], v[112:113], v[16:17]
	v_rcp_f32_e32 v25, v23
	v_max_f32_e32 v86, 0xda24260, v18
	v_max_f32_e32 v87, 0xda24260, v19
	v_pk_mul_f32 v[18:19], v[110:111], v[16:17]
	v_rcp_f32_e32 v44, v42
	v_max_f32_e32 v98, 0xda24260, v18
	v_max_f32_e32 v99, 0xda24260, v19
	v_rcp_f32_e32 v45, v43
	v_rcp_f32_e32 v88, v86
	v_rcp_f32_e32 v89, v87
	v_rcp_f32_e32 v108, v98
	v_rcp_f32_e32 v109, v99
	v_lshlrev_b32_e32 v26, 16, v192
	v_and_b32_e32 v27, 0xffff0000, v192
	v_lshlrev_b32_e32 v40, 16, v20
	v_and_b32_e32 v41, 0xffff0000, v20
	v_lshlrev_b32_e32 v48, 16, v119
	v_and_b32_e32 v49, 0xffff0000, v119
	v_lshlrev_b32_e32 v84, 16, v21
	v_and_b32_e32 v85, 0xffff0000, v21
	v_lshlrev_b32_e32 v90, 16, v118
	v_and_b32_e32 v91, 0xffff0000, v118
	v_lshlrev_b32_e32 v92, 16, v46
	v_and_b32_e32 v93, 0xffff0000, v46
	v_lshlrev_b32_e32 v110, 16, v191
	v_and_b32_e32 v111, 0xffff0000, v191
	v_lshlrev_b32_e32 v112, 16, v47
	v_and_b32_e32 v113, 0xffff0000, v47
	s_mov_b64 s[40:41], -1
	s_and_b64 vcc, exec, s[60:61]
	v_lshlrev_b32_e32 v96, 16, v120
	v_and_b32_e32 v97, 0xffff0000, v120
	v_lshlrev_b32_e32 v94, 16, v50
	v_and_b32_e32 v95, 0xffff0000, v50
	v_lshlrev_b32_e32 v50, 16, v121
	v_and_b32_e32 v51, 0xffff0000, v121
	v_lshlrev_b32_e32 v46, 16, v116
	v_and_b32_e32 v47, 0xffff0000, v116
	v_lshlrev_b32_e32 v18, 16, v193
	v_and_b32_e32 v19, 0xffff0000, v193
	v_lshlrev_b32_e32 v20, 16, v117
	v_and_b32_e32 v21, 0xffff0000, v117
	v_add_u32_e32 v199, 0x4800, v198
	v_add_u32_e32 v192, 0x400, v198
	v_add_u32_e32 v191, 0x4c00, v198
	s_cbranch_vccnz .LBB0_273
	v_pk_mul_f32 v[114:115], v[24:25], v[26:27]
	v_pk_mul_f32 v[116:117], v[22:23], v[40:41]
	v_cvt_pk_bf16_f32 v118, v114, v115
	v_pk_mul_f32 v[114:115], v[44:45], v[48:49]
	v_cvt_pk_bf16_f32 v195, v116, v117
	v_cvt_pk_bf16_f32 v114, v114, v115
	ds_write2_b32 v198, v118, v114 offset1:68
	v_pk_mul_f32 v[114:115], v[88:89], v[90:91]
	v_pk_mul_f32 v[116:117], v[42:43], v[84:85]
	v_cvt_pk_bf16_f32 v118, v114, v115
	v_pk_mul_f32 v[114:115], v[108:109], v[110:111]
	v_cvt_pk_bf16_f32 v193, v116, v117
	v_cvt_pk_bf16_f32 v114, v114, v115
	v_pk_mul_f32 v[116:117], v[86:87], v[92:93]
	ds_write2_b32 v198, v118, v114 offset0:136 offset1:204
	v_pk_mul_f32 v[114:115], v[36:37], v[16:17]
	v_cvt_pk_bf16_f32 v196, v116, v117
	v_pk_mul_f32 v[116:117], v[98:99], v[112:113]
	v_max_f32_e32 v114, 0xda24260, v114
	v_max_f32_e32 v115, 0xda24260, v115
	v_cvt_pk_bf16_f32 v197, v116, v117
	v_rcp_f32_e32 v116, v114
	v_rcp_f32_e32 v117, v115
	v_pk_mul_f32 v[114:115], v[114:115], v[94:95]
	s_mov_b64 s[40:41], 0
	v_cvt_pk_bf16_f32 v200, v114, v115
	v_pk_mul_f32 v[114:115], v[34:35], v[16:17]
	v_pk_mul_f32 v[116:117], v[116:117], v[96:97]
	v_max_f32_e32 v114, 0xda24260, v114
	v_max_f32_e32 v115, 0xda24260, v115
	v_cvt_pk_bf16_f32 v118, v116, v117
	v_rcp_f32_e32 v116, v114
	v_rcp_f32_e32 v117, v115
	v_pk_mul_f32 v[114:115], v[114:115], v[46:47]
	ds_write2_b32 v199, v195, v193 offset1:68
	v_cvt_pk_bf16_f32 v201, v114, v115
	v_pk_mul_f32 v[116:117], v[116:117], v[50:51]
	v_pk_mul_f32 v[114:115], v[32:33], v[16:17]
	v_cvt_pk_bf16_f32 v116, v116, v117
	ds_write2_b32 v192, v118, v116 offset0:16 offset1:84
	v_max_f32_e32 v116, 0xda24260, v114
	v_max_f32_e32 v117, 0xda24260, v115
	v_pk_mul_f32 v[118:119], v[38:39], v[16:17]
	v_rcp_f32_e32 v114, v116
	v_rcp_f32_e32 v115, v117
	v_max_f32_e32 v118, 0xda24260, v118
	v_max_f32_e32 v119, 0xda24260, v119
	v_rcp_f32_e32 v120, v118
	v_rcp_f32_e32 v121, v119
	v_pk_mul_f32 v[114:115], v[114:115], v[18:19]
	v_pk_mul_f32 v[116:117], v[116:117], v[20:21]
	ds_write2_b32 v199, v196, v197 offset0:136 offset1:204
	ds_write2_b32 v191, v200, v201 offset0:16 offset1:84
; #define LAS __attribute__((address_space(3)))
; #define LDS_BARRIER() do { asm volatile("s_waitcnt lgkmcnt(0)" ::: "memory"); __builtin_amdgcn_s_barrier(); asm volatile("" ::: "memory"); } while (0)
; #define MFMA16(a, b, c) __builtin_amdgcn_mfma_f32_16x16x32_bf16((a), (b), (c), 0, 0, 0)
; __device__ __forceinline__ void phase_hg2(Frame& F, int j, bool ctx_out, bool dry = false) {
;     ...
;                     if (seg >= 4) { HG_PASS2(small_, big_) } else { HG_PASS2(big_, small_) }
;     ...
;                     *(LAS v4u*)(KtT + (2 * c2) * HTS + seg * 8) = (v4u){k0[0] | (k0[1] << 16), k0[2] | (k0[3] << 16), k0[4] | (k0[5] << 16), k0[6] | (k0[7] << 16)};
;                     *(LAS v4u*)(KtT + (2 * c2 + 1) * HTS + seg * 8) = (v4u){k1[0] | (k1[1] << 16), k1[2] | (k1[3] << 16), k1[4] | (k1[5] << 16), k1[6] | (k1[7] << 16)};
;                 }
;                 LDS_BARRIER();
; #pragma unroll
;                 for (int kt = 0; kt < 8; ++kt) { const f32x4 e4 = *(const LAS f32x4*)(er + kt * 16 + q4 * 4); S[kt] = S[kt] * e4; }
; #pragma unroll
;                 for (int tl = 0; tl < 2; ++tl) { const int id = F.wave * 2 + tl, st = id >> 2, tt = id & 3;
;                     f32x4 a = (f32x4){0.f, 0.f, 0.f, 0.f};
;                     if (tt >= st) {
; #pragma unroll
;                         for (int ks = 0; ks < 4; ++ks) { const hb8 fa = *(const LAS hb8*)(Kt + (st * 16 + l15) * HQS + ks * 32 + q4 * 8), fb = *(const LAS hb8*)(Qt + (tt * 16 + l15) * HQS + ks * 32 + q4 * 8);
;                             a = MFMA16(fa, fb, a); }
.LBB0_273:
	s_andn2_b64 vcc, exec, s[40:41]
	s_cbranch_vccnz .LBB0_275
	v_pk_mul_f32 v[22:23], v[22:23], v[26:27]
	v_pk_mul_f32 v[24:25], v[24:25], v[40:41]
	v_cvt_pk_bf16_f32 v26, v22, v23
	v_pk_mul_f32 v[22:23], v[42:43], v[48:49]
	v_cvt_pk_bf16_f32 v195, v24, v25
	v_cvt_pk_bf16_f32 v22, v22, v23
	ds_write2_b32 v198, v26, v22 offset1:68
	v_pk_mul_f32 v[22:23], v[86:87], v[90:91]
	v_pk_mul_f32 v[24:25], v[44:45], v[84:85]
	v_cvt_pk_bf16_f32 v26, v22, v23
	v_pk_mul_f32 v[22:23], v[98:99], v[110:111]
	v_cvt_pk_bf16_f32 v193, v24, v25
	v_cvt_pk_bf16_f32 v22, v22, v23
	ds_write2_b32 v198, v26, v22 offset0:136 offset1:204
	v_pk_mul_f32 v[22:23], v[36:37], v[16:17]
	v_pk_mul_f32 v[24:25], v[88:89], v[92:93]
	v_max_f32_e32 v22, 0xda24260, v22
	v_max_f32_e32 v23, 0xda24260, v23
	v_rcp_f32_e32 v26, v22
	v_rcp_f32_e32 v27, v23
	v_cvt_pk_bf16_f32 v196, v24, v25
	v_pk_mul_f32 v[24:25], v[108:109], v[112:113]
	v_pk_mul_f32 v[22:23], v[22:23], v[96:97]
	v_cvt_pk_bf16_f32 v197, v24, v25
	v_pk_mul_f32 v[24:25], v[26:27], v[94:95]
	v_pk_mul_f32 v[26:27], v[34:35], v[16:17]
	v_cvt_pk_bf16_f32 v36, v22, v23
	v_max_f32_e32 v26, 0xda24260, v26
	v_max_f32_e32 v27, 0xda24260, v27
	v_rcp_f32_e32 v34, v26
	v_rcp_f32_e32 v35, v27
	v_pk_mul_f32 v[22:23], v[26:27], v[50:51]
	v_cvt_pk_bf16_f32 v200, v24, v25
	v_cvt_pk_bf16_f32 v22, v22, v23
	ds_write2_b32 v192, v36, v22 offset0:16 offset1:84
	v_pk_mul_f32 v[22:23], v[32:33], v[16:17]
	v_pk_mul_f32 v[24:25], v[34:35], v[46:47]
	v_max_f32_e32 v22, 0xda24260, v22
	v_max_f32_e32 v23, 0xda24260, v23
	v_pk_mul_f32 v[16:17], v[38:39], v[16:17]
	v_cvt_pk_bf16_f32 v201, v24, v25
	v_rcp_f32_e32 v24, v22
	v_rcp_f32_e32 v25, v23
	v_max_f32_e32 v120, 0xda24260, v16
	v_max_f32_e32 v121, 0xda24260, v17
	v_rcp_f32_e32 v118, v120
	v_rcp_f32_e32 v119, v121
	v_pk_mul_f32 v[114:115], v[22:23], v[18:19]
	v_pk_mul_f32 v[116:117], v[24:25], v[20:21]
	ds_write2_b32 v199, v195, v193 offset1:68
	ds_write2_b32 v199, v196, v197 offset0:136 offset1:204
	ds_write2_b32 v191, v200, v201 offset0:16 offset1:84
.LBB0_275:
	v_cndmask_b32_e64 v16, v29, v31, s[38:39]
	v_cndmask_b32_e64 v17, v28, v30, s[36:37]
	v_cvt_pk_bf16_f32 v19, v17, v16
	v_lshlrev_b32_e32 v16, 16, v190
	v_and_b32_e32 v17, 0xffff0000, v190
	v_pk_mul_f32 v[16:17], v[120:121], v[16:17]
	v_lshlrev_b32_e32 v18, 16, v19
	v_and_b32_e32 v19, 0xffff0000, v19
	v_cvt_pk_bf16_f32 v20, v114, v115
	v_cvt_pk_bf16_f32 v21, v116, v117
	v_pk_mul_f32 v[18:19], v[118:119], v[18:19]
	v_cvt_pk_bf16_f32 v16, v16, v17
	ds_write2_b32 v192, v20, v16 offset0:152 offset1:220
	v_cvt_pk_bf16_f32 v20, v18, v19
	v_and_b32_e32 v19, 0xffff, v21
	v_lshlrev_b32_e32 v16, 16, v193
	v_lshlrev_b32_e32 v17, 16, v197
	v_lshlrev_b32_e32 v18, 16, v201
	v_lshrrev_b32_e32 v22, 16, v195
	v_lshrrev_b32_e32 v23, 16, v196
	v_lshrrev_b32_e32 v24, 16, v200
	v_lshrrev_b32_e32 v25, 16, v21
	v_and_or_b32 v16, v195, s79, v16
	v_and_or_b32 v17, v196, s79, v17
	v_and_or_b32 v18, v200, s79, v18
	v_lshl_or_b32 v19, v20, 16, v19
	ds_write2_b32 v191, v21, v20 offset0:152 offset1:220
	ds_write_b128 v194, v[16:19] offset:36864
	v_and_or_b32 v16, v193, s77, v22
	v_and_or_b32 v17, v197, s77, v23
	v_and_or_b32 v18, v201, s77, v24
	v_and_or_b32 v19, v20, s77, v25
	ds_write_b128 v194, v[16:19] offset:37024
	v_lshlrev_b32_e32 v16, 4, v100
	v_add_u32_e32 v84, 0, v16
	s_waitcnt lgkmcnt(0)
	s_barrier
	v_add_u32_e32 v16, 0x1e800, v84
	ds_read_b128 v[40:43], v16
	ds_read_b128 v[44:47], v16 offset:64
	ds_read_b128 v[36:39], v16 offset:128
	ds_read_b128 v[32:35], v16 offset:192
	ds_read_b128 v[28:31], v16 offset:256
	ds_read_b128 v[24:27], v16 offset:320
	ds_read_b128 v[20:23], v16 offset:384
	ds_read_b128 v[16:19], v16 offset:448
	s_mov_b64 s[8:9], -1
	s_and_b64 vcc, exec, s[74:75]
	v_add_u32_e32 v85, s15, v177
	v_add_u32_e32 v86, s16, v177
	s_cbranch_vccz .LBB0_277
	v_mad_u64_u32 v[88:89], s[8:9], v85, s81, v[84:85]
	v_add_u32_e32 v90, s16, v177
	v_mad_u64_u32 v[108:109], s[8:9], v90, s81, v[84:85]
	ds_read_b128 v[208:211], v88 offset:18432
	ds_read_b128 v[212:215], v108
	ds_read_b128 v[216:219], v88 offset:18496
	ds_read_b128 v[220:223], v108 offset:64
	ds_read_b128 v[224:227], v88 offset:18560
	ds_read_b128 v[228:231], v108 offset:128
	ds_read_b128 v[232:235], v88 offset:18624
	ds_read_b128 v[236:239], v108 offset:192
	s_mov_b64 s[8:9], 0
	s_waitcnt lgkmcnt(6)
	v_mfma_f32_16x16x32_bf16 v[48:51], v[208:211], v[212:215], 0
	s_waitcnt lgkmcnt(4)
	v_mfma_f32_16x16x32_bf16 v[48:51], v[216:219], v[220:223], v[48:51]
	s_waitcnt lgkmcnt(2)
	v_mfma_f32_16x16x32_bf16 v[48:51], v[224:227], v[228:231], v[48:51]
	s_waitcnt lgkmcnt(0)
	v_mfma_f32_16x16x32_bf16 v[48:51], v[232:235], v[236:239], v[48:51]

; #define LAS __attribute__((address_space(3)))
; __device__ __forceinline__ unsigned pk2(float lo, float hi) { const f32x2_t v = {lo, hi}; return __builtin_bit_cast(unsigned, __builtin_convertvector(v, bf16x2_t)); }
; #define MFMA16(a, b, c) __builtin_amdgcn_mfma_f32_16x16x32_bf16((a), (b), (c), 0, 0, 0)
; __device__ __forceinline__ void phase_hg2(Frame& F, int j, bool ctx_out, bool dry = false) {
;     ...
;                     const int tg = tt * 16 + l15, sg = st * 16 + q4 * 4;
;                     const float a0 = (sg + 0 <= tg) ? a.x : 0.f, a1 = (sg + 1 <= tg) ? a.y : 0.f, a2 = (sg + 2 <= tg) ? a.z : 0.f, a3 = (sg + 3 <= tg) ? a.w : 0.f;
;                     *(LAS v2u*)(ATT + tg * HTS + sg) = (v2u){pk2(a0, a1), pk2(a2, a3)}; }
;                 f32x4 Oa[4];
; #pragma unroll
;                 for (int tt = 0; tt < 4; ++tt) Oa[tt] = (f32x4){0.f, 0.f, 0.f, 0.f};
; #pragma unroll
;                 for (int ks = 0; ks < 4; ++ks) {
;                     const v4u sb4 = (v4u){pk2(S[2 * ks].x, S[2 * ks].y), pk2(S[2 * ks].z, S[2 * ks].w), pk2(S[2 * ks + 1].x, S[2 * ks + 1].y), pk2(S[2 * ks + 1].z, S[2 * ks + 1].w)};
;                     const hb8 fb = __builtin_bit_cast(hb8, sb4);
; #pragma unroll
;                     for (int tt = 0; tt < 4; ++tt) { const v2u a0 = *(const LAS v2u*)(Qt + (tt * 16 + l15) * HQS + ks * 32 + q4 * 4), a1 = *(const LAS v2u*)(Qt + (tt * 16 + l15) * HQS + ks * 32 + 16 + q4 * 4);
;                         const v4u fa4 = (v4u){a0.x, a0.y, a1.x, a1.y}; Oa[tt] = MFMA16(__builtin_bit_cast(hb8, fa4), fb, Oa[tt]); } }
.LBB0_283:
	v_cmp_le_i32_e32 vcc, v87, v91
	s_waitcnt lgkmcnt(2)
	v_pk_mul_f32 v[20:21], v[52:53], v[20:21]
	v_mul_lo_u32 v52, v177, s81
	s_nop 1
	v_cndmask_b32_e32 v48, 0, v48, vcc
	v_cmp_lt_i32_e32 vcc, v87, v91
	v_lshlrev_b32_e32 v53, 1, v86
	v_pk_mul_f32 v[44:45], v[72:73], v[44:45]
	v_cndmask_b32_e32 v49, 0, v49, vcc
	v_cmp_le_i32_e32 vcc, v88, v91
	v_cvt_pk_bf16_f32 v48, v48, v49
	v_add3_u32 v72, 0, v52, v53
	v_cndmask_b32_e32 v50, 0, v50, vcc
	v_cmp_le_i32_e32 vcc, v89, v91
	v_pk_mul_f32 v[22:23], v[54:55], v[22:23]
	v_pk_mul_f32 v[46:47], v[74:75], v[46:47]
	v_cndmask_b32_e32 v51, 0, v51, vcc
	v_cvt_pk_bf16_f32 v49, v50, v51
	v_mul_lo_u32 v50, v91, s82
	v_add3_u32 v50, s83, v50, v90
	ds_write_b64 v50, v[48:49]
	ds_read_b64 v[52:53], v72
	ds_read_b64 v[54:55], v72 offset:32
	v_add_u32_e32 v73, 0x1000, v72
	v_add_u32_e32 v74, 0x2000, v72
	v_add_u32_e32 v75, 0x3000, v72
	v_pk_mul_f32 v[34:35], v[66:67], v[34:35]
	v_pk_mul_f32 v[32:33], v[64:65], v[32:33]
	v_pk_mul_f32 v[30:31], v[62:63], v[30:31]
	v_pk_mul_f32 v[28:29], v[60:61], v[28:29]
	v_pk_mul_f32 v[26:27], v[58:59], v[26:27]
	v_pk_mul_f32 v[24:25], v[56:57], v[24:25]
	ds_read_b64 v[56:57], v73 offset:256
	ds_read_b64 v[58:59], v73 offset:288
	ds_read_b64 v[60:61], v74 offset:512
	ds_read_b64 v[62:63], v74 offset:544
	ds_read_b64 v[64:65], v75 offset:768
	ds_read_b64 v[66:67], v75 offset:800
	v_pk_mul_f32 v[38:39], v[70:71], v[38:39]
	v_pk_mul_f32 v[36:37], v[68:69], v[36:37]
	ds_read_b64 v[68:69], v72 offset:64
	ds_read_b64 v[70:71], v72 offset:96
	v_pk_mul_f32 v[42:43], v[78:79], v[42:43]
	v_pk_mul_f32 v[40:41], v[76:77], v[40:41]
	v_cvt_pk_bf16_f32 v49, v42, v43
	v_cvt_pk_bf16_f32 v48, v40, v41
	v_cvt_pk_bf16_f32 v50, v44, v45
	v_cvt_pk_bf16_f32 v51, v46, v47
	s_waitcnt lgkmcnt(12)
	v_pk_mul_f32 v[18:19], v[82:83], v[18:19]
	v_pk_mul_f32 v[16:17], v[80:81], v[16:17]
	s_waitcnt lgkmcnt(8)
	v_mfma_f32_16x16x32_bf16 v[52:55], v[52:55], v[48:51], 0
	v_lshlrev_b32_e32 v85, 3, v100
	v_mul_lo_u32 v76, v177, s82
	v_add_u32_e32 v80, 0xa00, v76
	s_waitcnt lgkmcnt(6)
	v_mfma_f32_16x16x32_bf16 v[56:59], v[56:59], v[48:51], 0
	v_add_u32_e32 v87, 0x1400, v76
	v_add_u32_e32 v88, 0x1e00, v76
	v_add_u32_e32 v99, v84, v76
	s_waitcnt lgkmcnt(4)
	v_mfma_f32_16x16x32_bf16 v[60:63], v[60:63], v[48:51], 0
	v_add_u32_e32 v112, v84, v80
	v_add_u32_e32 v113, v84, v87
	v_add_u32_e32 v114, v84, v88
	s_waitcnt lgkmcnt(2)
	v_mfma_f32_16x16x32_bf16 v[48:51], v[64:67], v[48:51], 0
	v_cvt_pk_bf16_f32 v64, v36, v37
	v_cvt_pk_bf16_f32 v65, v38, v39
	v_cvt_pk_bf16_f32 v66, v32, v33
	v_cvt_pk_bf16_f32 v67, v34, v35
	s_movk_i32 s8, 0x840
	s_and_b64 vcc, exec, s[6:7]
	s_waitcnt lgkmcnt(0)
	v_mfma_f32_16x16x32_bf16 v[52:55], v[68:71], v[64:67], v[52:55]
	ds_read_b64 v[68:69], v73 offset:320
	ds_read_b64 v[70:71], v73 offset:352
	s_waitcnt lgkmcnt(0)
	v_mfma_f32_16x16x32_bf16 v[56:59], v[68:71], v[64:67], v[56:59]
	ds_read_b64 v[68:69], v74 offset:576
	ds_read_b64 v[70:71], v74 offset:608
	s_waitcnt lgkmcnt(0)
	v_mfma_f32_16x16x32_bf16 v[60:63], v[68:71], v[64:67], v[60:63]
	ds_read_b64 v[68:69], v75 offset:832
	ds_read_b64 v[70:71], v75 offset:864
	s_waitcnt lgkmcnt(0)
	v_mfma_f32_16x16x32_bf16 v[48:51], v[68:71], v[64:67], v[48:51]
	ds_read_b64 v[68:69], v72 offset:128
	ds_read_b64 v[70:71], v72 offset:160
	v_cvt_pk_bf16_f32 v64, v28, v29
	v_cvt_pk_bf16_f32 v65, v30, v31
	v_cvt_pk_bf16_f32 v66, v24, v25
	v_cvt_pk_bf16_f32 v67, v26, v27
	s_waitcnt lgkmcnt(0)
	s_nop 0
	v_mfma_f32_16x16x32_bf16 v[52:55], v[68:71], v[64:67], v[52:55]
	ds_read_b64 v[68:69], v73 offset:384
	ds_read_b64 v[70:71], v73 offset:416
	s_waitcnt lgkmcnt(0)
	v_mfma_f32_16x16x32_bf16 v[56:59], v[68:71], v[64:67], v[56:59]
	ds_read_b64 v[68:69], v74 offset:640
	ds_read_b64 v[70:71], v74 offset:672
	s_waitcnt lgkmcnt(0)
	v_mfma_f32_16x16x32_bf16 v[60:63], v[68:71], v[64:67], v[60:63]
	ds_read_b64 v[68:69], v75 offset:896
	ds_read_b64 v[70:71], v75 offset:928
	s_waitcnt lgkmcnt(0)
	v_mfma_f32_16x16x32_bf16 v[48:51], v[68:71], v[64:67], v[48:51]
	ds_read_b64 v[68:69], v72 offset:192
	ds_read_b64 v[70:71], v72 offset:224
	v_cvt_pk_bf16_f32 v64, v20, v21
	v_cvt_pk_bf16_f32 v65, v22, v23
	v_cvt_pk_bf16_f32 v66, v16, v17
	v_cvt_pk_bf16_f32 v67, v18, v19
	s_waitcnt lgkmcnt(0)
	s_nop 0
	v_mfma_f32_16x16x32_bf16 v[52:55], v[68:71], v[64:67], v[52:55]
	ds_read_b64 v[68:69], v73 offset:448
	ds_read_b64 v[70:71], v73 offset:480
	s_waitcnt lgkmcnt(0)
	v_mfma_f32_16x16x32_bf16 v[56:59], v[68:71], v[64:67], v[56:59]
	ds_read_b64 v[68:69], v74 offset:704
	ds_read_b64 v[70:71], v74 offset:736
	s_waitcnt lgkmcnt(0)
	v_mfma_f32_16x16x32_bf16 v[60:63], v[68:71], v[64:67], v[60:63]
	ds_read_b64 v[68:69], v75 offset:960
	ds_read_b64 v[70:71], v75 offset:992
	s_waitcnt lgkmcnt(0)
	s_barrier
; #define LAS __attribute__((address_space(3)))
; #define LDS_BARRIER() do { asm volatile("s_waitcnt lgkmcnt(0)" ::: "memory"); __builtin_amdgcn_s_barrier(); asm volatile("" ::: "memory"); } while (0)
; #define MFMA16(a, b, c) __builtin_amdgcn_mfma_f32_16x16x32_bf16((a), (b), (c), 0, 0, 0)
; __device__ __forceinline__ void phase_hg2(Frame& F, int j, bool ctx_out, bool dry = false) {
;     ...
; #pragma unroll
;                 for (int ss = 0; ss < 2; ++ss) { const hb8 fb = *(const LAS hb8*)(VT + (vb * 16 + l15) * HTS + ss * 32 + q4 * 8);
; #pragma unroll
;                     for (int tt = 0; tt < 4; ++tt) { const hb8 fa = *(const LAS hb8*)(ATT + (tt * 16 + l15) * HTS + ss * 32 + q4 * 8); Oa[tt] = MFMA16(fa, fb, Oa[tt]); }
; #pragma unroll
;                     for (int kt = 0; kt < 8; ++kt) { const hb8 fa = *(const LAS hb8*)(KtT + (kt * 16 + l15) * HTS + ss * 32 + q4 * 8); S[kt] = MFMA16(fa, fb, S[kt]); } }
; #pragma unroll
;                 for (int kt = 0; kt < 8; ++kt) { const f32x4 e4 = *(const LAS f32x4*)(eend + kt * 16 + q4 * 4); S[kt] = S[kt] * e4; }
; #pragma unroll
;                 for (int tt = 0; tt < 4; ++tt) {
; #pragma unroll
;                     for (int i = 0; i < 4; ++i) O32[(tt * 16 + q4 * 4 + i) * HOS + vb * 16 + l15] = Oa[tt][i]; }
;                 LDS_BARRIER();
;                 {
;                     f32x4 o[4];
; #pragma unroll
;                     for (int u = 0; u < 4; ++u) o[u] = *(const LAS f32x4*)(O32 + rto * HOS + g8o * 16 + u * 4);
	s_waitcnt lgkmcnt(0)
	v_mfma_f32_16x16x32_bf16 v[48:51], v[68:71], v[64:67], v[48:51]
	v_add_u32_e32 v64, s12, v177
	v_lshlrev_b32_e32 v65, 1, v85
	v_mul_lo_u32 v64, v64, s82
	v_add_u32_e32 v72, s83, v65
	v_add3_u32 v85, 0, v64, v65
	v_add_u32_e32 v86, v72, v76
	v_add_u32_e32 v90, v72, v80
	v_add_u32_e32 v94, v72, v87
	v_add_u32_e32 v98, v72, v88
	ds_read_b128 v[240:243], v85 offset:57344
	ds_read_b128 v[208:211], v86
	ds_read_b128 v[212:215], v90
	ds_read_b128 v[216:219], v94
	ds_read_b128 v[220:223], v98
	ds_read_b128 v[224:227], v99 offset:36864
	ds_read_b128 v[228:231], v112 offset:36864
	ds_read_b128 v[232:235], v113 offset:36864
	ds_read_b128 v[236:239], v114 offset:36864
	s_waitcnt lgkmcnt(7)
	v_mfma_f32_16x16x32_bf16 v[68:71], v[208:211], v[240:243], v[52:55]
	ds_read_b128 v[208:211], v99 offset:47104
	s_waitcnt lgkmcnt(7)
	v_mfma_f32_16x16x32_bf16 v[56:59], v[212:215], v[240:243], v[56:59]
	ds_read_b128 v[212:215], v99 offset:49664
	s_waitcnt lgkmcnt(7)
	v_mfma_f32_16x16x32_bf16 v[60:63], v[216:219], v[240:243], v[60:63]
	ds_read_b128 v[216:219], v99 offset:52224
	s_waitcnt lgkmcnt(7)
	v_mfma_f32_16x16x32_bf16 v[72:75], v[220:223], v[240:243], v[48:51]
	ds_read_b128 v[220:223], v99 offset:54784
	s_waitcnt lgkmcnt(7)
	v_mfma_f32_16x16x32_bf16 v[76:79], v[224:227], v[240:243], v[40:43]
	ds_read_b128 v[244:247], v85 offset:57408
	ds_read_b128 v[224:227], v86 offset:64
	s_waitcnt lgkmcnt(8)
	v_mfma_f32_16x16x32_bf16 v[80:83], v[228:231], v[240:243], v[44:47]
	ds_read_b128 v[228:231], v114 offset:36928
	s_waitcnt lgkmcnt(8)
	v_mfma_f32_16x16x32_bf16 v[52:55], v[232:235], v[240:243], v[36:39]
	ds_read_b128 v[232:235], v90 offset:64
	s_waitcnt lgkmcnt(8)
	v_mfma_f32_16x16x32_bf16 v[48:51], v[236:239], v[240:243], v[32:35]
	ds_read_b128 v[236:239], v99 offset:47168
	s_waitcnt lgkmcnt(8)
	v_mfma_f32_16x16x32_bf16 v[32:35], v[208:211], v[240:243], v[28:31]
	ds_read_b128 v[208:211], v94 offset:64
	s_waitcnt lgkmcnt(8)
	v_mfma_f32_16x16x32_bf16 v[36:39], v[212:215], v[240:243], v[24:27]
	ds_read_b128 v[212:215], v99 offset:49728
	s_waitcnt lgkmcnt(8)
	v_mfma_f32_16x16x32_bf16 v[40:43], v[216:219], v[240:243], v[20:23]
	ds_read_b128 v[216:219], v98 offset:64
	s_waitcnt lgkmcnt(8)
	v_mfma_f32_16x16x32_bf16 v[44:47], v[220:223], v[240:243], v[16:19]
	ds_read_b128 v[220:223], v99 offset:52288
	s_waitcnt lgkmcnt(7)
	v_mfma_f32_16x16x32_bf16 v[86:89], v[224:227], v[244:247], v[68:71]
	ds_read_b128 v[224:227], v112 offset:36928
	s_waitcnt lgkmcnt(7)
	v_mfma_f32_16x16x32_bf16 v[28:31], v[228:231], v[244:247], v[48:51]
	ds_read_b128 v[228:231], v99 offset:54848
	s_waitcnt lgkmcnt(7)
	v_mfma_f32_16x16x32_bf16 v[90:93], v[232:235], v[244:247], v[56:59]
	ds_read_b128 v[232:235], v99 offset:36928
	s_waitcnt lgkmcnt(7)
	v_mfma_f32_16x16x32_bf16 v[32:35], v[236:239], v[244:247], v[32:35]
	ds_read_b128 v[236:239], v113 offset:36928
	s_waitcnt lgkmcnt(7)
	v_mfma_f32_16x16x32_bf16 v[94:97], v[208:211], v[244:247], v[60:63]
	s_waitcnt lgkmcnt(6)
	v_mfma_f32_16x16x32_bf16 v[36:39], v[212:215], v[244:247], v[36:39]
	s_waitcnt lgkmcnt(5)
	v_mfma_f32_16x16x32_bf16 v[108:111], v[216:219], v[244:247], v[72:75]
	s_waitcnt lgkmcnt(4)
	v_mfma_f32_16x16x32_bf16 v[40:43], v[220:223], v[244:247], v[40:43]
	s_waitcnt lgkmcnt(3)
	v_mfma_f32_16x16x32_bf16 v[20:23], v[224:227], v[244:247], v[80:83]
	s_waitcnt lgkmcnt(2)
	v_mfma_f32_16x16x32_bf16 v[44:47], v[228:231], v[244:247], v[44:47]
	s_waitcnt lgkmcnt(1)
	v_mfma_f32_16x16x32_bf16 v[16:19], v[232:235], v[244:247], v[76:79]
	s_waitcnt lgkmcnt(0)
	v_mfma_f32_16x16x32_bf16 v[24:27], v[236:239], v[244:247], v[52:55]
	v_lshlrev_b32_e32 v80, 2, v177
	v_mul_lo_u32 v81, v100, s8
	v_add3_u32 v80, s14, v80, v81
	v_add_u32_e32 v48, 0x1ea00, v84
	v_add_u32_e32 v81, 0x400, v80
	s_movk_i32 s8, 0x210
	s_nop 1
	ds_read_b128 v[76:79], v48
	ds_read_b128 v[72:75], v48 offset:64
	ds_read_b128 v[68:71], v48 offset:128
	ds_read_b128 v[64:67], v48 offset:192
	ds_read_b128 v[60:63], v48 offset:256
	ds_read_b128 v[56:59], v48 offset:320
	ds_read_b128 v[52:55], v48 offset:384
	ds_read_b128 v[48:51], v48 offset:448
	ds_write2_b32 v81, v88, v89 offset0:8 offset1:140
	v_add_u32_e32 v81, 0x2000, v80
	ds_write2_b32 v81, v90, v91 offset0:64 offset1:196
	v_add_u32_e32 v81, 0x2400, v80
	ds_write2_b32 v81, v92, v93 offset0:72 offset1:204
	v_add_u32_e32 v81, 0x4200, v80
	ds_write2_b32 v81, v94, v95 offset1:132
	v_add_u32_e32 v81, 0x4600, v80
	ds_write2_b32 v80, v86, v87 offset1:132
	ds_write2_b32 v81, v96, v97 offset0:8 offset1:140
	v_add_u32_e32 v81, 0x6200, v80
	v_add_u32_e32 v80, 0x6600, v80
	ds_write2_b32 v81, v108, v109 offset0:64 offset1:196
	ds_write2_b32 v80, v110, v111 offset0:72 offset1:204
	v_mul_lo_u32 v80, v189, s8
	v_lshlrev_b32_e32 v81, 2, v188
	s_waitcnt lgkmcnt(0)
	s_barrier
	v_add3_u32 v80, 0, v80, v81
	ds_read_b128 v[92:95], v80
	ds_read_b128 v[88:91], v80 offset:16
	ds_read_b128 v[84:87], v80 offset:32
	ds_read_b128 v[80:83], v80 offset:48
	s_cbranch_vccz .LBB0_288
; #define GAS __attribute__((address_space(1)))
; #define LAS __attribute__((address_space(3)))
; __device__ __forceinline__ unsigned pk2(float lo, float hi) { const f32x2_t v = {lo, hi}; return __builtin_bit_cast(unsigned, __builtin_convertvector(v, bf16x2_t)); }
; __device__ __forceinline__ float sum8(float x) { x += dppf<0xB1>(x); x += dppf<0x4E>(x); x += dppf<0x141>(x); return x; }
; __device__ __forceinline__ void phase_hg2(Frame& F, int j, bool ctx_out, bool dry = false) {
;     ...
;                     } else if (do_out) {
;                         float ss = 0.f;
; #pragma unroll
;                         for (int u2 = 0; u2 < 2; ++u2) { const v4u f = pf[u2];
;                             o[2 * u2] = o[2 * u2] + (f32x4){bflo(f.x), bfhi(f.x), bflo(f.y), bfhi(f.y)}; o[2 * u2 + 1] = o[2 * u2 + 1] + (f32x4){bflo(f.z), bfhi(f.z), bflo(f.w), bfhi(f.w)}; }
; #pragma unroll
;                         for (int u = 0; u < 4; ++u) ss += (o[u].x * o[u].x + o[u].y * o[u].y) + (o[u].z * o[u].z + o[u].w * o[u].w);
;                         ss = sum8(ss);
;                         const float r = __builtin_amdgcn_rsqf(ss * (1.f / 128.f) + RMS_EPS);
;                         GAS v4u* gp = (GAS v4u*)((GAS char*)(P + 4 * DM + h * 128) + ((unsigned)rrow * HG_N + g8o * 16) * 2u);
; #pragma unroll
;                         for (int u2 = 0; u2 < 2; ++u2) { const v4u rg = pg[u2]; const f32x4 oa = o[2 * u2], ob2 = o[2 * u2 + 1]; const f32x4 nga = *(const LAS f32x4*)(s_ng + g8o * 16 + u2 * 8), ngb = *(const LAS f32x4*)(s_ng + g8o * 16 + u2 * 8 + 4); const float ngp[8] = {nga.x, nga.y, nga.z, nga.w, ngb.x, ngb.y, ngb.z, ngb.w};
;                             const float y0 = oa.x * r * ngp[0] * bflo(rg.x), y1 = oa.y * r * ngp[1] * bfhi(rg.x), y2 = oa.z * r * ngp[2] * bflo(rg.y), y3 = oa.w * r * ngp[3] * bfhi(rg.y);
;                             const float y4 = ob2.x * r * ngp[4] * bflo(rg.z), y5 = ob2.y * r * ngp[5] * bfhi(rg.z), y6 = ob2.z * r * ngp[6] * bflo(rg.w), y7 = ob2.w * r * ngp[7] * bfhi(rg.w);
;                             gp[u2] = (v4u){pk2(y0, y1), pk2(y2, y3), pk2(y4, y5), pk2(y6, y7)}; }
	s_mov_b64 s[36:37], 0
	s_and_b64 vcc, exec, s[0:1]
	s_mov_b64 s[38:39], 0
	s_cbranch_vccz .LBB0_286
	s_waitcnt vmcnt(26)
	v_lshlrev_b32_e32 v96, 16, v12
	v_and_b32_e32 v97, 0xffff0000, v12
	v_lshlrev_b32_e32 v12, 16, v13
	v_and_b32_e32 v13, 0xffff0000, v13
	s_waitcnt lgkmcnt(3)
	v_pk_add_f32 v[116:117], v[94:95], v[12:13]
	v_lshlrev_b32_e32 v12, 16, v14
	v_and_b32_e32 v13, 0xffff0000, v14
	s_waitcnt lgkmcnt(2)
	v_pk_add_f32 v[118:119], v[88:89], v[12:13]
	v_lshlrev_b32_e32 v12, 16, v8
	v_and_b32_e32 v13, 0xffff0000, v8
	v_lshlrev_b32_e32 v8, 16, v9
	v_and_b32_e32 v9, 0xffff0000, v9
	v_pk_add_f32 v[114:115], v[92:93], v[96:97]
	s_waitcnt lgkmcnt(1)
	v_pk_add_f32 v[190:191], v[86:87], v[8:9]
	v_lshlrev_b32_e32 v8, 16, v10
	v_and_b32_e32 v9, 0xffff0000, v10
	v_lshlrev_b32_e32 v10, 16, v11
	v_and_b32_e32 v11, 0xffff0000, v11
	v_lshlrev_b32_e32 v14, 16, v15
	v_and_b32_e32 v15, 0xffff0000, v15
	s_waitcnt lgkmcnt(0)
	v_pk_add_f32 v[194:195], v[82:83], v[10:11]
	v_pk_add_f32 v[196:197], v[80:81], v[8:9]
	v_pk_mul_f32 v[8:9], v[116:117], v[116:117]
	v_pk_mul_f32 v[10:11], v[114:115], v[114:115]
	v_pk_add_f32 v[120:121], v[90:91], v[14:15]
	v_pk_add_f32 v[192:193], v[84:85], v[12:13]
	v_pk_mov_b32 v[12:13], v[10:11], v[8:9] op_sel:[1,0]
	v_mov_b32_e32 v11, v9
	v_pk_add_f32 v[8:9], v[12:13], v[10:11]
	v_pk_mul_f32 v[10:11], v[120:121], v[120:121]
	v_pk_mul_f32 v[12:13], v[118:119], v[118:119]
	v_pk_add_f32 v[8:9], v[8:9], v[8:9] op_sel:[0,1] op_sel_hi:[1,0]
	v_pk_mov_b32 v[14:15], v[12:13], v[10:11] op_sel:[1,0]
	v_mov_b32_e32 v13, v11
	v_pk_add_f32 v[10:11], v[14:15], v[12:13]
	v_mul_f32_e32 v12, v196, v196
	v_mul_f32_e32 v13, v197, v197
	v_pk_add_f32 v[10:11], v[10:11], v[10:11] op_sel:[0,1] op_sel_hi:[1,0]
	v_mov_b32_e32 v9, v12
	v_mov_b32_e32 v11, v13
	v_pk_add_f32 v[8:9], v[8:9], v[10:11]
	v_mul_f32_e32 v10, v193, v193
	v_mul_f32_e32 v12, v191, v191
	v_mul_f32_e32 v14, v194, v194
	v_mul_f32_e32 v15, v195, v195
	v_pk_fma_f32 v[10:11], v[192:193], v[192:193], v[10:11] op_sel_hi:[1,1,0]
	v_pk_fma_f32 v[12:13], v[190:191], v[190:191], v[12:13] op_sel_hi:[1,1,0]
	v_mov_b32_e32 v11, v14
	v_mov_b32_e32 v13, v15
	v_pk_add_f32 v[10:11], v[10:11], v[12:13]
	s_mov_b64 s[38:39], -1
	v_pk_add_f32 v[8:9], v[8:9], v[10:11]
	s_nop 0
	v_add_f32_e32 v8, v8, v9
	s_nop 1
	v_add_f32_dpp v8, v8, v8 quad_perm:[1,0,3,2] row_mask:0xf bank_mask:0xf bound_ctrl:1
	s_nop 1
	v_add_f32_dpp v8, v8, v8 quad_perm:[2,3,0,1] row_mask:0xf bank_mask:0xf bound_ctrl:1
	s_nop 1
	v_add_f32_dpp v8, v8, v8 row_half_mirror row_mask:0xf bank_mask:0xf bound_ctrl:1
	v_fmamk_f32 v8, v8, 0x3c000000, v160
	v_rsq_f32_e32 v198, v8
	v_mul_lo_u32 v8, v182, s80
	v_add_lshl_u32 v100, v8, v188, 1
	v_lshl_add_u32 v8, v188, 2, 0
	v_add_u32_e32 v110, 0x20000, v8
	ds_read_b128 v[8:11], v110
	ds_read_b128 v[12:15], v110 offset:16
	ds_read_b128 v[96:99], v110 offset:32
	ds_read_b128 v[110:113], v110 offset:48
	v_pk_mul_f32 v[114:115], v[114:115], v[198:199] op_sel_hi:[1,0]
	v_lshl_add_u64 v[108:109], s[34:35], 0, v[100:101]
	s_waitcnt lgkmcnt(3)
	v_pk_mul_f32 v[8:9], v[8:9], v[114:115]
	s_waitcnt vmcnt(24)
	v_lshlrev_b32_e32 v114, 16, v4
	v_and_b32_e32 v115, 0xffff0000, v4
	v_pk_mul_f32 v[8:9], v[8:9], v[114:115]
	v_pk_mul_f32 v[114:115], v[116:117], v[198:199] op_sel_hi:[1,0]
	v_lshlrev_b32_e32 v4, 16, v5
	v_pk_mul_f32 v[10:11], v[10:11], v[114:115]
	v_and_b32_e32 v5, 0xffff0000, v5
	v_pk_mul_f32 v[10:11], v[10:11], v[4:5]
	v_pk_mul_f32 v[4:5], v[118:119], v[198:199] op_sel_hi:[1,0]
	s_waitcnt lgkmcnt(2)
	v_pk_mul_f32 v[4:5], v[12:13], v[4:5]
	v_lshlrev_b32_e32 v12, 16, v6
	v_and_b32_e32 v13, 0xffff0000, v6
	v_pk_mul_f32 v[12:13], v[4:5], v[12:13]
	v_pk_mul_f32 v[4:5], v[120:121], v[198:199] op_sel_hi:[1,0]
	v_lshlrev_b32_e32 v6, 16, v7
	v_pk_mul_f32 v[4:5], v[14:15], v[4:5]
	v_and_b32_e32 v7, 0xffff0000, v7
	v_pk_mul_f32 v[14:15], v[4:5], v[6:7]
	v_cvt_pk_bf16_f32 v4, v8, v9
	v_cvt_pk_bf16_f32 v5, v10, v11
	v_cvt_pk_bf16_f32 v6, v12, v13
	v_cvt_pk_bf16_f32 v7, v14, v15
	global_store_dwordx4 v100, v[4:7], s[34:35]
	v_lshlrev_b32_e32 v8, 16, v2
	v_and_b32_e32 v9, 0xffff0000, v2
	v_pk_mul_f32 v[4:5], v[192:193], v[198:199] op_sel_hi:[1,0]
	v_lshlrev_b32_e32 v6, 16, v0
	s_waitcnt lgkmcnt(1)
	v_pk_mul_f32 v[4:5], v[96:97], v[4:5]
	v_and_b32_e32 v7, 0xffff0000, v0
	v_pk_mul_f32 v[4:5], v[4:5], v[6:7]
	v_pk_mul_f32 v[6:7], v[190:191], v[198:199] op_sel_hi:[1,0]
	v_lshlrev_b32_e32 v0, 16, v1
	v_pk_mul_f32 v[6:7], v[98:99], v[6:7]
	v_and_b32_e32 v1, 0xffff0000, v1
	v_pk_mul_f32 v[0:1], v[6:7], v[0:1]
	v_pk_mul_f32 v[6:7], v[196:197], v[198:199] op_sel_hi:[1,0]
	v_lshlrev_b32_e32 v2, 16, v3
	s_waitcnt lgkmcnt(0)
	v_pk_mul_f32 v[6:7], v[6:7], v[110:111]
	v_and_b32_e32 v3, 0xffff0000, v3
	v_pk_mul_f32 v[6:7], v[6:7], v[8:9]
	v_pk_mul_f32 v[8:9], v[194:195], v[198:199] op_sel_hi:[1,0]
	v_cvt_pk_bf16_f32 v96, v4, v5
	v_pk_mul_f32 v[8:9], v[8:9], v[112:113]
	v_cvt_pk_bf16_f32 v97, v0, v1
	v_pk_mul_f32 v[110:111], v[8:9], v[2:3]
	v_cvt_pk_bf16_f32 v98, v6, v7
	s_and_b64 vcc, exec, s[36:37]
	s_cbranch_vccz .LBB0_289
	s_branch .LBB0_287

; #define LAS __attribute__((address_space(3)))
; #define LDS_BARRIER() do { asm volatile("s_waitcnt lgkmcnt(0)" ::: "memory"); __builtin_amdgcn_s_barrier(); asm volatile("" ::: "memory"); } while (0)
; #define FRAME_TID(F) do { (F).lane = pg8::lane_id_asm(); (F).tid = (F).wave * 64 + (F).lane; } while (0)
; __device__ __forceinline__ void phase_gdn2(Frame& F, bool ctx_out, bool dry = false) {
;     FRAME_TID(F);
;     gb P = (gb)(F.ws + WS_P); gb OB = (gb)(F.ws + WS_O); gb KT = (gb)(F.ws + WS_H);
;     gcf alog = F.in[I_GDNALOG]; gcf dtb = F.in[I_GDNDTB]; gcf ng = F.in[I_GDNNG];
;     LAS bf16* KC = (LAS bf16*)(F.lds + GD_KC); LAS bf16* QC = (LAS bf16*)(F.lds + GD_QC); LAS bf16* KCT = (LAS bf16*)(F.lds + GD_KCT); LAS bf16* VT = (LAS bf16*)(F.lds + GD_VT);
;     LAS bf16* O16 = (LAS bf16*)(F.lds + GD_O16);
;     LAS bf16* TUB = (LAS bf16*)(F.lds + GD_TUB); LAS bf16* TWB = (LAS bf16*)(F.lds + GD_TWB); LAS bf16* QKB = (LAS bf16*)(F.lds + GD_QKB);
;     LAS float* LB = (LAS float*)(F.lds + GD_LB); LAS float* s_ng = (LAS float*)(F.lds + 151552);
;     LAS float* s_gate0 = (LAS float*)(F.lds + GD_SC);
;     LAS float* s_ckd = s_gate0 + 416; LAS float* s_rq = s_ckd + 64; LAS float* s_rk = s_rq + 64;
;     LAS bf16* W = KC;
;     const int vb = F.wave;
;     const int tid_ = F.tid, lane_ = F.lane;
;     for (int item2 = blockIdx.x; item2 < NB * 16; item2 += F.G) {
;       gdn_conv_sweep(F, item2 >> 4, item2 & 15);
;       for (int ev = 0; ev < 2; ++ev) {
;         const int item = item2 * 2 + ev;
;         const int b = item >> 5, hv = item & 31, hq = hv >> 1;
;         LDS_BARRIER();
;         for (int i = tid_; i < 3 * 5120 / 16; i += NTHREADS) ((LAS v4u*)(F.lds + GD_TUB))[i] = (v4u){0u, 0u, 0u, 0u};
;         if (tid_ < 128) s_ng[tid_] = ng[tid_];
;         for (int i = tid_; i < 256 * 2; i += NTHREADS) { const int r = i >> 1, hh = i & 1; LAS bf16* img = (r < 128) ? KCT : VT; *(LAS v4u*)(img + (r & 127) * GT + 64 + hh * 8) = (v4u){0u, 0u, 0u, 0u}; }
;         for (int d = 0; d < 2; ++d) {
;             const float dtbv = dtb[d * 32 + hv], aexp = __expf(alog[d * 32 + hv]);
;             f32x4 S[8];
; #pragma unroll
;             for (int kt = 0; kt < 8; ++kt) S[kt] = (f32x4){0.f, 0.f, 0.f, 0.f};
;             v4u rawp[8]; unsigned short gpb_ = 0, gpa_ = 0;
.LBB0_867:
	s_cmp_gt_i32 s52, 11
	s_cselect_b64 s[0:1], -1, 0
	s_cmp_lt_i32 s53, 12
	s_cselect_b64 s[2:3], -1, 0
	s_or_b64 s[0:1], s[0:1], s[2:3]
	s_and_b64 vcc, exec, s[0:1]
	s_cbranch_vccnz .LBB0_1081
	s_cmpk_gt_i32 s73, 0xff
	v_mbcnt_lo_u32_b32 v118, -1, 0
	v_mbcnt_hi_u32_b32 v118, -1, v118
	s_cbranch_scc1 .LBB0_1031
	s_load_dwordx2 s[2:3], s[94:95], 0xd8
	v_readlane_b32 s0, v254, 0
	v_readlane_b32 s4, v254, 37
	v_readlane_b32 s5, v254, 38
	v_add_u32_e32 v112, s0, v118
	s_waitcnt lgkmcnt(0)
	s_add_u32 s34, s2, 0xa700000
	s_addc_u32 s35, s3, 0
	s_add_u32 s0, s2, 0x41900000
	v_writelane_b32 v255, s0, 19
	s_addc_u32 s0, s3, 0
	v_writelane_b32 v255, s0, 21
	s_add_u32 s0, s2, 0x53900000
	v_writelane_b32 v255, s0, 11
	s_addc_u32 s0, s3, 0
	v_writelane_b32 v255, s0, 12
	s_mov_b64 s[0:1], s[4:5]
	v_mov_b32_e32 v0, s0
	s_movk_i32 s0, 0x3c0
	v_mov_b32_e32 v1, s1
	v_cmp_gt_i32_e64 s[0:1], s0, v112
	s_movk_i32 s60, 0x80
	v_readlane_b32 s6, v254, 39
	v_writelane_b32 v255, s0, 23
	v_readlane_b32 s7, v254, 40
	v_readlane_b32 s8, v254, 41
	v_writelane_b32 v255, s1, 24
	v_cmp_gt_i32_e64 s[0:1], s60, v112
	v_readlane_b32 s9, v254, 42
	v_readlane_b32 s10, v254, 43
	v_writelane_b32 v255, s0, 25
	v_readlane_b32 s11, v254, 44
	v_readlane_b32 s12, v254, 45
	v_writelane_b32 v255, s1, 26
	s_add_i32 s0, 0, 0x25000
	v_lshl_add_u32 v119, v112, 2, s0
	s_movk_i32 s0, 0x200
	v_cmp_gt_i32_e64 s[0:1], s0, v112
	v_readlane_b32 s13, v254, 46
	v_readlane_b32 s14, v254, 47
	v_writelane_b32 v255, s0, 27
	v_readlane_b32 s15, v254, 48
	v_readlane_b32 s16, v254, 49
	v_writelane_b32 v255, s1, 28
	v_readlane_b32 s0, v254, 57
	s_cmp_lt_u32 s0, 64
	v_readlane_b32 s17, v254, 50
	v_readlane_b32 s18, v254, 51
	v_readlane_b32 s19, v254, 52
	s_mov_b64 s[4:5], s[8:9]
	s_cselect_b64 s[38:39], -1, 0
	s_cmp_gt_u32 s0, 63
	s_cselect_b64 s[4:5], -1, 0
	s_lshl_b32 s58, s33, 3
	v_writelane_b32 v255, s4, 13
	s_add_i32 s59, s58, -8
	s_add_u32 s1, s2, 0xa704000
	v_writelane_b32 v255, s5, 14
	v_writelane_b32 v255, s1, 31
	s_addc_u32 s1, s3, 0
	s_cmpk_gt_u32 s0, 0xff
	s_cselect_b64 s[42:43], -1, 0
	s_add_i32 s62, 0, 0x4400
	s_cmpk_lt_u32 s0, 0x100
	s_cselect_b32 s64, 0, s62
	s_lshl_b32 s0, s33, 5
	s_lshl_b32 s65, s33, 4
	s_add_i32 s67, s0, 0
	s_and_b32 s66, s65, 48
	s_add_i32 s89, s67, 0x1b000
	s_cmp_eq_u32 s33, 7
	v_ashrrev_i32_e32 v113, 31, v112
	v_writelane_b32 v255, s1, 5
	s_cselect_b64 s[0:1], -1, 0
	v_lshl_add_u64 v[114:115], v[112:113], 2, v[0:1]
	v_writelane_b32 v255, s0, 15
	v_lshlrev_b32_e32 v0, 1, v112
	v_and_b32_e32 v113, 0x1fe, v0
	v_writelane_b32 v255, s1, 16
	s_movk_i32 s0, 0x7f
	v_cmp_lt_u32_e64 s[0:1], s0, v113
	s_mov_b64 s[6:7], s[10:11]
	s_mov_b64 s[8:9], s[12:13]
	v_writelane_b32 v255, s0, 29
	s_mov_b64 s[10:11], s[14:15]
	v_mov_b32_e32 v2, 0
	v_writelane_b32 v255, s1, 30
	s_movk_i32 s0, 0xff
	v_cmp_lt_u32_e64 s[0:1], s0, v113
	s_mov_b64 s[12:13], s[16:17]
	s_mov_b64 s[14:15], s[18:19]
	v_writelane_b32 v255, s0, 33
	s_mov_b32 s37, 0
	v_add_u32_e32 v120, 0xf00, v113
	v_writelane_b32 v255, s1, 34
	s_lshl_b32 s0, s33, 10
	s_add_i32 s0, s0, 0
	v_lshl_add_u32 v0, v118, 4, s0
	s_add_i32 s0, 0, 0x19000
	v_writelane_b32 v255, s0, 7
	v_add_u32_e32 v123, 0x1f400, v0
	v_lshlrev_b32_e32 v0, 3, v118
	v_readlane_b32 s0, v255, 2
	v_add_u32_e32 v121, 0x780, v113
	v_add_u32_e32 v122, 0xfffffe00, v112
	v_lshl_add_u32 v124, s33, 9, v0
	s_movk_i32 s90, 0x6200
	s_movk_i32 s92, 0x2000
	s_movk_i32 s97, 0x1bf
	s_movk_i32 s10, 0x90
	s_movk_i32 s11, 0x3100
	s_mov_b32 s8, 0x41a00000
	s_mov_b32 s9, 0x3f2aaaab
	v_mov_b32_e32 v125, 0x3ecc95a3
	s_mov_b32 s87, 0x3f317218
	s_mov_b32 s88, 0x7f800000
	s_mov_b32 s91, 0x33800000
	s_add_i32 s93, 0, 0x24400
	s_movk_i32 s57, 0x7c0
	s_movk_i32 s44, 0x110
	s_add_i32 s45, 0, 0x24b80
	s_add_i32 s40, 0, 0x24c80
	s_movk_i32 s84, 0x50
	s_add_i32 s85, 0, 0x21c00
	s_add_i32 s63, 0, 0x23000
	v_mov_b32_e32 v126, 0x358637bd
	s_add_i32 s47, 0, 0x20800
	v_mov_b32_e32 v148, v2
	v_mov_b32_e32 v149, v2
	v_mov_b32_e32 v150, v2
	v_mov_b32_e32 v151, v2
	v_mov_b32_e32 v127, 0xd800
	v_mov_b32_e32 v128, 0x8800
	v_mov_b32_e32 v116, 0x3f317218
	v_mov_b32_e32 v129, 0x7f800000
	v_mov_b32_e32 v130, 0x7fc00000
	v_mov_b32_e32 v131, 0xff800000
	v_mov_b32_e32 v132, 0xfffff900
	s_mov_b32 s6, s0
	s_mov_b32 s46, 0xbfb8aa3b
	s_mov_b64 s[48:49], 0x6000
	s_branch .LBB0_871

; __device__ __forceinline__ void phase_gdn2(Frame& F, bool ctx_out, bool dry = false) {
;     ...
;                 f32x4 U[4];
; #pragma unroll
;                 for (int I = 0; I < 4; ++I) {
;                     const hb8 fa = *(const LAS hb8*)(TUB + (I * 16 + l15) * GB + q4 * 8), fb = *(const LAS hb8*)(VT + (vb * 16 + l15) * GT + I * 16 + q4 * 8);
;                     U[I] = MFMA16(fa, fb, ((f32x4){0.f, 0.f, 0.f, 0.f}));
;                     const hb8 ga = *(const LAS hb8*)(KCT + (vb * 16 + l15) * GT + I * 16 + q4 * 8), gbv = *(const LAS hb8*)(TWB + (I * 16 + l15) * GB + q4 * 8);
;                     const f32x4 wt = MFMA16(ga, gbv, ((f32x4){0.f, 0.f, 0.f, 0.f}));
;                     *(LAS v2u*)(W + (I * 16 + l15) * GS + vb * 16 + q4 * 4) = (v2u){pk2(-wt.x, -wt.y), pk2(-wt.z, -wt.w)};
;                 }
;                 LDS_WAIT(); asm volatile("" ::: "memory");
;                 LDS_BARRIER();
; #pragma unroll
;                 for (int I = 0; I < 4; ++I) {
;                     f32x4 vn = U[I], oa = (f32x4){0.f, 0.f, 0.f, 0.f};
; #pragma unroll
;                     for (int ks = 0; ks < 4; ++ks) {
;                         const v4u sb4 = (v4u){pk2(S[2 * ks].x, S[2 * ks].y), pk2(S[2 * ks].z, S[2 * ks].w), pk2(S[2 * ks + 1].x, S[2 * ks + 1].y), pk2(S[2 * ks + 1].z, S[2 * ks + 1].w)};
;                         const hb8 fb = __builtin_bit_cast(hb8, sb4);
;                         const v2u w0 = *(const LAS v2u*)(W + (I * 16 + l15) * GS + ks * 32 + q4 * 4), w1 = *(const LAS v2u*)(W + (I * 16 + l15) * GS + ks * 32 + 16 + q4 * 4);
;                         const v2u q0 = *(const LAS v2u*)(QC + (I * 16 + l15) * GS + ks * 32 + q4 * 4), q1 = *(const LAS v2u*)(QC + (I * 16 + l15) * GS + ks * 32 + 16 + q4 * 4);
;                         const v4u fw4 = (v4u){w0.x, w0.y, w1.x, w1.y}, fq4 = (v4u){q0.x, q0.y, q1.x, q1.y};
;                         vn = MFMA16(__builtin_bit_cast(hb8, fw4), fb, vn); oa = MFMA16(__builtin_bit_cast(hb8, fq4), fb, oa); }
;                     const f32x4 ck = *(const LAS f32x4*)(s_ckd + I * 16 + q4 * 4), eg = *(const LAS f32x4*)(s_eG + I * 16 + q4 * 4), rqv = *(const LAS f32x4*)(s_rq + I * 16 + q4 * 4);
;                     const v4u vn4 = (v4u){pk2(vn.x, vn.y), pk2(vn.z, vn.w), 0u, 0u}, vp4 = (v4u){pk2(vn.x * ck.x, vn.y * ck.y), pk2(vn.z * ck.z, vn.w * ck.w), 0u, 0u};
;                     oa = oa * eg;
.Lgdn_drained:
	v_add3_u32 v88, s0, v0, v1
	v_add3_u32 v89, s47, v0, v1
	ds_read_b128 v[154:157], v88
	ds_read_b128 v[158:161], v3 offset:55296
	ds_read_b128 v[162:165], v3 offset:34816
	ds_read_b128 v[166:169], v89
	ds_read_b128 v[170:173], v88 offset:1280
	ds_read_b128 v[174:177], v3 offset:55328
	ds_read_b128 v[178:181], v3 offset:34848
	ds_read_b128 v[182:185], v89 offset:1280
	ds_read_b128 v[186:189], v88 offset:2560
	ds_read_b128 v[190:193], v3 offset:55360
	ds_read_b128 v[194:197], v3 offset:34880
	ds_read_b128 v[198:201], v89 offset:2560
	ds_read_b128 v[202:205], v88 offset:3840
	ds_read_b128 v[206:209], v3 offset:55392
	ds_read_b128 v[210:213], v3 offset:34912
	ds_read_b128 v[214:217], v89 offset:3840
	v_add_u32_e32 v108, 0, v139
	v_add_u32_e32 v107, s76, v140
	v_add_u32_e32 v101, s85, v139
	v_mul_u32_u24_e32 v84, 0x110, v137
	v_add3_u32 v92, s67, v139, v84
	v_mad_u32_u24 v103, v137, s10, v108
	v_or_b32_e32 v110, 16, v137
	v_mad_u32_u24 v104, v110, s10, v108
	v_or_b32_e32 v109, 32, v137
	v_or_b32_e32 v100, 48, v137
	s_add_i32 s56, s56, 1
	s_add_i32 s3, s3, 64
	s_add_i32 s96, s96, 1
	s_cmpk_eq_i32 s3, 0x900
	s_waitcnt lgkmcnt(14)
	v_mfma_f32_16x16x32_bf16 v[68:71], v[154:157], v[158:161], 0
	s_waitcnt lgkmcnt(12)
	v_mfma_f32_16x16x32_bf16 v[218:221], v[162:165], v[166:169], 0
	s_waitcnt lgkmcnt(10)
	v_mfma_f32_16x16x32_bf16 v[80:83], v[170:173], v[174:177], 0
	s_waitcnt lgkmcnt(8)
	v_mfma_f32_16x16x32_bf16 v[222:225], v[178:181], v[182:185], 0
	s_waitcnt lgkmcnt(6)
	v_mfma_f32_16x16x32_bf16 v[76:79], v[186:189], v[190:193], 0
	s_waitcnt lgkmcnt(4)
	v_mfma_f32_16x16x32_bf16 v[226:229], v[194:197], v[198:201], 0
	s_waitcnt lgkmcnt(2)
	v_mfma_f32_16x16x32_bf16 v[72:75], v[202:205], v[206:209], 0
	s_waitcnt lgkmcnt(0)
	v_mfma_f32_16x16x32_bf16 v[230:233], v[210:213], v[214:217], 0
	v_xor_b32_e32 v0, 0x80000000, v219
	v_xor_b32_e32 v1, 0x80000000, v218
	v_cvt_pk_bf16_f32 v0, v1, v0
	v_xor_b32_e32 v1, 0x80000000, v220
	v_xor_b32_e32 v84, 0x80000000, v221
	v_cvt_pk_bf16_f32 v1, v1, v84
	ds_write_b64 v92, v[0:1]
	v_xor_b32_e32 v0, 0x80000000, v223
	v_xor_b32_e32 v1, 0x80000000, v222
	v_cvt_pk_bf16_f32 v0, v1, v0
	v_xor_b32_e32 v1, 0x80000000, v224
	v_xor_b32_e32 v84, 0x80000000, v225
	v_cvt_pk_bf16_f32 v1, v1, v84
	ds_write_b64 v92, v[0:1] offset:4352
	v_xor_b32_e32 v0, 0x80000000, v227
	v_xor_b32_e32 v1, 0x80000000, v226
	v_cvt_pk_bf16_f32 v0, v1, v0
	v_xor_b32_e32 v1, 0x80000000, v228
	v_xor_b32_e32 v84, 0x80000000, v229
	v_cvt_pk_bf16_f32 v1, v1, v84
	ds_write_b64 v92, v[0:1] offset:8704
	v_xor_b32_e32 v0, 0x80000000, v231
	v_xor_b32_e32 v1, 0x80000000, v230
	v_cvt_pk_bf16_f32 v0, v1, v0
	v_xor_b32_e32 v1, 0x80000000, v232
	v_xor_b32_e32 v84, 0x80000000, v233
	v_cvt_pk_bf16_f32 v1, v1, v84
	ds_write_b64 v92, v[0:1] offset:13056
	v_add_u32_e32 v0, 0, v140
	s_waitcnt lgkmcnt(0)
	v_add_u32_e32 v106, 0x24a80, v0
	v_add_u32_e32 v102, 0x24b80, v0
	v_mul_u32_u24_e32 v0, 0x88, v137
	v_lshl_add_u32 v0, v0, 1, v108
	s_waitcnt lgkmcnt(0)
	s_barrier
	v_mov_b32_e32 v218, 0
	v_mov_b32_e32 v219, 0
	v_mov_b32_e32 v234, 0
	v_mov_b32_e32 v235, 0
	v_mov_b32_e32 v242, 0
	v_mov_b32_e32 v243, 0
	v_mov_b32_e32 v246, 0
	v_mov_b32_e32 v247, 0
	v_mov_b32_e32 v250, s76
	ds_read_b128 v[236:239], v250 offset:768
	ds_read_b64 v[154:155], v0
	ds_read_b64 v[156:157], v0 offset:32
	ds_read_b64 v[170:171], v0 offset:17408
	ds_read_b64 v[172:173], v0 offset:17440
	ds_read_b64 v[158:159], v0 offset:64
	ds_read_b64 v[160:161], v0 offset:96
	ds_read_b64 v[174:175], v0 offset:17472
	ds_read_b64 v[176:177], v0 offset:17504
	v_mad_u32_u24 v252, v137, s84, v101
	v_lshlrev_b32_e32 v92, 1, v137
	v_mul_u32_u24_e32 v93, 0x440, v138
	v_add3_u32 v253, s89, v92, v93
	v_cvt_pk_bf16_f32 v186, v36, v37
	v_cvt_pk_bf16_f32 v187, v38, v39
	v_cvt_pk_bf16_f32 v188, v40, v41
	v_cvt_pk_bf16_f32 v189, v42, v43
	ds_read_b64 v[162:163], v0 offset:128
	ds_read_b64 v[164:165], v0 offset:160
	ds_read_b64 v[178:179], v0 offset:17536
	ds_read_b64 v[180:181], v0 offset:17568
	s_waitcnt lgkmcnt(8)
	v_mfma_f32_16x16x32_bf16 v[68:71], v[154:157], v[186:189], v[68:71]
	v_mfma_f32_16x16x32_bf16 v[84:87], v[170:173], v[186:189], 0
	v_cvt_pk_bf16_f32 v190, v44, v45
	v_cvt_pk_bf16_f32 v191, v46, v47
	v_cvt_pk_bf16_f32 v192, v48, v49
	v_cvt_pk_bf16_f32 v193, v50, v51
	ds_read_b64 v[166:167], v0 offset:192
	ds_read_b64 v[168:169], v0 offset:224
	ds_read_b64 v[182:183], v0 offset:17600
	ds_read_b64 v[184:185], v0 offset:17632
	s_waitcnt lgkmcnt(8)
	v_mfma_f32_16x16x32_bf16 v[68:71], v[158:161], v[190:193], v[68:71]
	v_mfma_f32_16x16x32_bf16 v[84:87], v[174:177], v[190:193], v[84:87]
	v_cvt_pk_bf16_f32 v194, v52, v53
	v_cvt_pk_bf16_f32 v195, v54, v55
	v_cvt_pk_bf16_f32 v196, v56, v57
	v_cvt_pk_bf16_f32 v197, v58, v59
	ds_read_b64 v[202:203], v103 offset:34816
	ds_read_b64 v[204:205], v104 offset:34816
	ds_read_b64 v[206:207], v104 offset:37120
	ds_read_b64 v[208:209], v104 offset:39424
	s_waitcnt lgkmcnt(8)
	v_mfma_f32_16x16x32_bf16 v[68:71], v[162:165], v[194:197], v[68:71]
	v_mfma_f32_16x16x32_bf16 v[84:87], v[178:181], v[194:197], v[84:87]
	v_cvt_pk_bf16_f32 v198, v60, v61
	v_cvt_pk_bf16_f32 v199, v62, v63
	v_cvt_pk_bf16_f32 v200, v64, v65
	v_cvt_pk_bf16_f32 v201, v66, v67
	ds_read_b64 v[210:211], v103 offset:44032
	ds_read_b64 v[212:213], v103 offset:46336
	ds_read_b64 v[214:215], v103 offset:48640
	ds_read_b64 v[216:217], v103 offset:50944
	s_waitcnt lgkmcnt(8)
; #define LAS __attribute__((address_space(3)))
; __device__ __forceinline__ void phase_gdn2(Frame& F, bool ctx_out, bool dry = false) {
;     ...
;                 for (int I = 0; I < 4; ++I) {
;                     f32x4 vn = U[I], oa = (f32x4){0.f, 0.f, 0.f, 0.f};
; #pragma unroll
;                     for (int ks = 0; ks < 4; ++ks) {
;                         const v4u sb4 = (v4u){pk2(S[2 * ks].x, S[2 * ks].y), pk2(S[2 * ks].z, S[2 * ks].w), pk2(S[2 * ks + 1].x, S[2 * ks + 1].y), pk2(S[2 * ks + 1].z, S[2 * ks + 1].w)};
;                         const hb8 fb = __builtin_bit_cast(hb8, sb4);
;                         const v2u w0 = *(const LAS v2u*)(W + (I * 16 + l15) * GS + ks * 32 + q4 * 4), w1 = *(const LAS v2u*)(W + (I * 16 + l15) * GS + ks * 32 + 16 + q4 * 4);
;                         const v2u q0 = *(const LAS v2u*)(QC + (I * 16 + l15) * GS + ks * 32 + q4 * 4), q1 = *(const LAS v2u*)(QC + (I * 16 + l15) * GS + ks * 32 + 16 + q4 * 4);
;                         const v4u fw4 = (v4u){w0.x, w0.y, w1.x, w1.y}, fq4 = (v4u){q0.x, q0.y, q1.x, q1.y};
;                         vn = MFMA16(__builtin_bit_cast(hb8, fw4), fb, vn); oa = MFMA16(__builtin_bit_cast(hb8, fq4), fb, oa); }
;                     const f32x4 ck = *(const LAS f32x4*)(s_ckd + I * 16 + q4 * 4), eg = *(const LAS f32x4*)(s_eG + I * 16 + q4 * 4), rqv = *(const LAS f32x4*)(s_rq + I * 16 + q4 * 4);
;                     const v4u vn4 = (v4u){pk2(vn.x, vn.y), pk2(vn.z, vn.w), 0u, 0u}, vp4 = (v4u){pk2(vn.x * ck.x, vn.y * ck.y), pk2(vn.z * ck.z, vn.w * ck.w), 0u, 0u};
;                     oa = oa * eg;
;                     { const v2u a0 = *(const LAS v2u*)(QKB + (I * 16 + l15) * GB + q4 * 4); const v4u fa4 = (v4u){a0.x, a0.y, 0u, 0u}; oa = MFMA16(__builtin_bit_cast(hb8, fa4), __builtin_bit_cast(hb8, vn4), oa); }
;                     oa = oa * rqv;
; #pragma unroll
;                     for (int i = 0; i < 4; ++i) O16[(I * 16 + q4 * 4 + i) * GS + vb * 16 + l15] = (bf16)f2bf(oa[i]);
;                     const float ege = s_eGend[I];
;                     const hb8 fbn = __builtin_bit_cast(hb8, vp4);
; #pragma unroll
;                     for (int kt = 0; kt < 8; ++kt) { const v2u a0 = *(const LAS v2u*)(KCT + (kt * 16 + l15) * GT + I * 16 + q4 * 4); const v4u fa4 = (v4u){a0.x, a0.y, 0u, 0u}; S[kt] = MFMA16(__builtin_bit_cast(hb8, fa4), fbn, S[kt] * ege); }
	v_mfma_f32_16x16x32_bf16 v[68:71], v[166:169], v[198:201], v[68:71]
	v_mfma_f32_16x16x32_bf16 v[84:87], v[182:185], v[198:201], v[84:87]
	ds_read_b128 v[220:223], v106
	ds_read_b128 v[224:227], v107 offset:512
	ds_read_b128 v[228:231], v102
	ds_read_b64 v[232:233], v252
	v_pk_mul_f32 v[36:37], v[36:37], v[236:237] op_sel_hi:[1,0]
	v_pk_mul_f32 v[38:39], v[38:39], v[236:237] op_sel_hi:[1,0]
	v_pk_mul_f32 v[40:41], v[40:41], v[236:237] op_sel_hi:[1,0]
	v_pk_mul_f32 v[42:43], v[42:43], v[236:237] op_sel_hi:[1,0]
	v_pk_mul_f32 v[44:45], v[44:45], v[236:237] op_sel_hi:[1,0]
	v_pk_mul_f32 v[46:47], v[46:47], v[236:237] op_sel_hi:[1,0]
	v_pk_mul_f32 v[48:49], v[48:49], v[236:237] op_sel_hi:[1,0]
	v_pk_mul_f32 v[50:51], v[50:51], v[236:237] op_sel_hi:[1,0]
	v_pk_mul_f32 v[52:53], v[52:53], v[236:237] op_sel_hi:[1,0]
	v_pk_mul_f32 v[54:55], v[54:55], v[236:237] op_sel_hi:[1,0]
	v_pk_mul_f32 v[56:57], v[56:57], v[236:237] op_sel_hi:[1,0]
	v_pk_mul_f32 v[58:59], v[58:59], v[236:237] op_sel_hi:[1,0]
	v_pk_mul_f32 v[60:61], v[60:61], v[236:237] op_sel_hi:[1,0]
	v_pk_mul_f32 v[62:63], v[62:63], v[236:237] op_sel_hi:[1,0]
	v_pk_mul_f32 v[64:65], v[64:65], v[236:237] op_sel_hi:[1,0]
	v_pk_mul_f32 v[66:67], v[66:67], v[236:237] op_sel_hi:[1,0]
	s_waitcnt lgkmcnt(2)
	v_cvt_pk_bf16_f32 v240, v68, v69
	v_cvt_pk_bf16_f32 v241, v70, v71
	v_pk_mul_f32 v[88:89], v[68:69], v[220:221]
	v_pk_mul_f32 v[90:91], v[70:71], v[222:223]
	v_cvt_pk_bf16_f32 v244, v88, v89
	v_cvt_pk_bf16_f32 v245, v90, v91
	v_pk_mul_f32 v[84:85], v[84:85], v[224:225]
	v_pk_mul_f32 v[86:87], v[86:87], v[226:227]
	s_waitcnt lgkmcnt(0)
	v_mfma_f32_16x16x32_bf16 v[36:39], v[202:205], v[244:247], v[36:39]
	v_mfma_f32_16x16x32_bf16 v[40:43], v[204:207], v[244:247], v[40:43]
	v_mfma_f32_16x16x32_bf16 v[84:87], v[232:235], v[240:243], v[84:87]
	v_add_u32_e32 v250, 4352, v0
	v_mfma_f32_16x16x32_bf16 v[44:47], v[206:209], v[244:247], v[44:47]
	v_mfma_f32_16x16x32_bf16 v[48:51], v[208:211], v[244:247], v[48:51]
	v_mfma_f32_16x16x32_bf16 v[52:55], v[210:213], v[244:247], v[52:55]
	v_mfma_f32_16x16x32_bf16 v[56:59], v[212:215], v[244:247], v[56:59]
	v_mfma_f32_16x16x32_bf16 v[60:63], v[214:217], v[244:247], v[60:63]
	v_mfma_f32_16x16x32_bf16 v[64:67], v[216:219], v[244:247], v[64:67]
	ds_read_b64 v[154:155], v250
	ds_read_b64 v[156:157], v250 offset:32
	ds_read_b64 v[170:171], v250 offset:17408
	ds_read_b64 v[172:173], v250 offset:17440
	ds_read_b64 v[158:159], v250 offset:64
	ds_read_b64 v[160:161], v250 offset:96
	ds_read_b64 v[174:175], v250 offset:17472
	ds_read_b64 v[176:177], v250 offset:17504
	v_pk_mul_f32 v[84:85], v[84:85], v[228:229]
	v_pk_mul_f32 v[86:87], v[86:87], v[230:231]
	v_cvt_pk_bf16_f32 v88, v84, v85
	v_cvt_pk_bf16_f32 v90, v86, v87
	v_lshrrev_b32_e32 v89, 16, v88
	v_lshrrev_b32_e32 v91, 16, v90
	ds_write_b16 v253, v88
	ds_write_b16 v253, v89 offset:272
	ds_write_b16 v253, v90 offset:544
	ds_write_b16 v253, v91 offset:816
	v_cvt_pk_bf16_f32 v186, v36, v37
	v_cvt_pk_bf16_f32 v187, v38, v39
	v_cvt_pk_bf16_f32 v188, v40, v41
	v_cvt_pk_bf16_f32 v189, v42, v43
	s_waitcnt lgkmcnt(8)
	ds_read_b64 v[162:163], v250 offset:128
	ds_read_b64 v[164:165], v250 offset:160
	ds_read_b64 v[178:179], v250 offset:17536
	ds_read_b64 v[180:181], v250 offset:17568
	s_waitcnt lgkmcnt(8)
	v_mfma_f32_16x16x32_bf16 v[80:83], v[154:157], v[186:189], v[80:83]
	v_mfma_f32_16x16x32_bf16 v[84:87], v[170:173], v[186:189], 0
	v_cvt_pk_bf16_f32 v190, v44, v45
	v_cvt_pk_bf16_f32 v191, v46, v47
	v_cvt_pk_bf16_f32 v192, v48, v49
	v_cvt_pk_bf16_f32 v193, v50, v51
	ds_read_b64 v[166:167], v250 offset:192
	ds_read_b64 v[168:169], v250 offset:224
	ds_read_b64 v[182:183], v250 offset:17600
	ds_read_b64 v[184:185], v250 offset:17632
	s_waitcnt lgkmcnt(8)
	v_mfma_f32_16x16x32_bf16 v[80:83], v[158:161], v[190:193], v[80:83]
	v_mfma_f32_16x16x32_bf16 v[84:87], v[174:177], v[190:193], v[84:87]
	v_cvt_pk_bf16_f32 v194, v52, v53
	v_cvt_pk_bf16_f32 v195, v54, v55
	v_cvt_pk_bf16_f32 v196, v56, v57
	v_cvt_pk_bf16_f32 v197, v58, v59
	ds_read_b64 v[202:203], v103 offset:34848
	ds_read_b64 v[204:205], v104 offset:34848
	ds_read_b64 v[206:207], v104 offset:37152
	ds_read_b64 v[208:209], v104 offset:39456
	s_waitcnt lgkmcnt(8)
	v_mfma_f32_16x16x32_bf16 v[80:83], v[162:165], v[194:197], v[80:83]
	v_mfma_f32_16x16x32_bf16 v[84:87], v[178:181], v[194:197], v[84:87]
	v_cvt_pk_bf16_f32 v198, v60, v61
	v_cvt_pk_bf16_f32 v199, v62, v63
	v_cvt_pk_bf16_f32 v200, v64, v65
	v_cvt_pk_bf16_f32 v201, v66, v67
	ds_read_b64 v[210:211], v103 offset:44064
	ds_read_b64 v[212:213], v103 offset:46368
	ds_read_b64 v[214:215], v103 offset:48672
	ds_read_b64 v[216:217], v103 offset:50976
	s_waitcnt lgkmcnt(8)
	v_mfma_f32_16x16x32_bf16 v[80:83], v[166:169], v[198:201], v[80:83]
	v_mfma_f32_16x16x32_bf16 v[84:87], v[182:185], v[198:201], v[84:87]
	ds_read_b128 v[220:223], v106 offset:64
	ds_read_b128 v[224:227], v107 offset:576
	ds_read_b128 v[228:231], v102 offset:64
	ds_read_b64 v[232:233], v252 offset:1280
	v_pk_mul_f32 v[36:37], v[36:37], v[236:237] op_sel:[0,1]
	v_pk_mul_f32 v[38:39], v[38:39], v[236:237] op_sel:[0,1]
	v_pk_mul_f32 v[40:41], v[40:41], v[236:237] op_sel:[0,1]
	v_pk_mul_f32 v[42:43], v[42:43], v[236:237] op_sel:[0,1]
	v_pk_mul_f32 v[44:45], v[44:45], v[236:237] op_sel:[0,1]
	v_pk_mul_f32 v[46:47], v[46:47], v[236:237] op_sel:[0,1]
	v_pk_mul_f32 v[48:49], v[48:49], v[236:237] op_sel:[0,1]
	v_pk_mul_f32 v[50:51], v[50:51], v[236:237] op_sel:[0,1]
	v_pk_mul_f32 v[52:53], v[52:53], v[236:237] op_sel:[0,1]
	v_pk_mul_f32 v[54:55], v[54:55], v[236:237] op_sel:[0,1]
	v_pk_mul_f32 v[56:57], v[56:57], v[236:237] op_sel:[0,1]
	v_pk_mul_f32 v[58:59], v[58:59], v[236:237] op_sel:[0,1]
	v_pk_mul_f32 v[60:61], v[60:61], v[236:237] op_sel:[0,1]
	v_pk_mul_f32 v[62:63], v[62:63], v[236:237] op_sel:[0,1]
	v_pk_mul_f32 v[64:65], v[64:65], v[236:237] op_sel:[0,1]
	v_pk_mul_f32 v[66:67], v[66:67], v[236:237] op_sel:[0,1]
	s_waitcnt lgkmcnt(2)
; #define LAS __attribute__((address_space(3)))
; __device__ __forceinline__ void phase_gdn2(Frame& F, bool ctx_out, bool dry = false) {
;     ...
;                 for (int I = 0; I < 4; ++I) {
;                     f32x4 vn = U[I], oa = (f32x4){0.f, 0.f, 0.f, 0.f};
; #pragma unroll
;                     for (int ks = 0; ks < 4; ++ks) {
;                         const v4u sb4 = (v4u){pk2(S[2 * ks].x, S[2 * ks].y), pk2(S[2 * ks].z, S[2 * ks].w), pk2(S[2 * ks + 1].x, S[2 * ks + 1].y), pk2(S[2 * ks + 1].z, S[2 * ks + 1].w)};
;                         const hb8 fb = __builtin_bit_cast(hb8, sb4);
;                         const v2u w0 = *(const LAS v2u*)(W + (I * 16 + l15) * GS + ks * 32 + q4 * 4), w1 = *(const LAS v2u*)(W + (I * 16 + l15) * GS + ks * 32 + 16 + q4 * 4);
;                         const v2u q0 = *(const LAS v2u*)(QC + (I * 16 + l15) * GS + ks * 32 + q4 * 4), q1 = *(const LAS v2u*)(QC + (I * 16 + l15) * GS + ks * 32 + 16 + q4 * 4);
;                         const v4u fw4 = (v4u){w0.x, w0.y, w1.x, w1.y}, fq4 = (v4u){q0.x, q0.y, q1.x, q1.y};
;                         vn = MFMA16(__builtin_bit_cast(hb8, fw4), fb, vn); oa = MFMA16(__builtin_bit_cast(hb8, fq4), fb, oa); }
;                     const f32x4 ck = *(const LAS f32x4*)(s_ckd + I * 16 + q4 * 4), eg = *(const LAS f32x4*)(s_eG + I * 16 + q4 * 4), rqv = *(const LAS f32x4*)(s_rq + I * 16 + q4 * 4);
;                     const v4u vn4 = (v4u){pk2(vn.x, vn.y), pk2(vn.z, vn.w), 0u, 0u}, vp4 = (v4u){pk2(vn.x * ck.x, vn.y * ck.y), pk2(vn.z * ck.z, vn.w * ck.w), 0u, 0u};
;                     oa = oa * eg;
;                     { const v2u a0 = *(const LAS v2u*)(QKB + (I * 16 + l15) * GB + q4 * 4); const v4u fa4 = (v4u){a0.x, a0.y, 0u, 0u}; oa = MFMA16(__builtin_bit_cast(hb8, fa4), __builtin_bit_cast(hb8, vn4), oa); }
;                     oa = oa * rqv;
; #pragma unroll
;                     for (int i = 0; i < 4; ++i) O16[(I * 16 + q4 * 4 + i) * GS + vb * 16 + l15] = (bf16)f2bf(oa[i]);
;                     const float ege = s_eGend[I];
;                     const hb8 fbn = __builtin_bit_cast(hb8, vp4);
; #pragma unroll
;                     for (int kt = 0; kt < 8; ++kt) { const v2u a0 = *(const LAS v2u*)(KCT + (kt * 16 + l15) * GT + I * 16 + q4 * 4); const v4u fa4 = (v4u){a0.x, a0.y, 0u, 0u}; S[kt] = MFMA16(__builtin_bit_cast(hb8, fa4), fbn, S[kt] * ege); }
	v_cvt_pk_bf16_f32 v240, v80, v81
	v_cvt_pk_bf16_f32 v241, v82, v83
	v_pk_mul_f32 v[88:89], v[80:81], v[220:221]
	v_pk_mul_f32 v[90:91], v[82:83], v[222:223]
	v_cvt_pk_bf16_f32 v244, v88, v89
	v_cvt_pk_bf16_f32 v245, v90, v91
	v_pk_mul_f32 v[84:85], v[84:85], v[224:225]
	v_pk_mul_f32 v[86:87], v[86:87], v[226:227]
	s_waitcnt lgkmcnt(0)
	v_mfma_f32_16x16x32_bf16 v[36:39], v[202:205], v[244:247], v[36:39]
	v_mfma_f32_16x16x32_bf16 v[40:43], v[204:207], v[244:247], v[40:43]
	v_mfma_f32_16x16x32_bf16 v[84:87], v[232:235], v[240:243], v[84:87]
	v_add_u32_e32 v250, 8704, v0
	v_mfma_f32_16x16x32_bf16 v[44:47], v[206:209], v[244:247], v[44:47]
	v_mfma_f32_16x16x32_bf16 v[48:51], v[208:211], v[244:247], v[48:51]
	v_mfma_f32_16x16x32_bf16 v[52:55], v[210:213], v[244:247], v[52:55]
	v_mfma_f32_16x16x32_bf16 v[56:59], v[212:215], v[244:247], v[56:59]
	v_mfma_f32_16x16x32_bf16 v[60:63], v[214:217], v[244:247], v[60:63]
	v_mfma_f32_16x16x32_bf16 v[64:67], v[216:219], v[244:247], v[64:67]
	ds_read_b64 v[154:155], v250
	ds_read_b64 v[156:157], v250 offset:32
	ds_read_b64 v[170:171], v250 offset:17408
	ds_read_b64 v[172:173], v250 offset:17440
	ds_read_b64 v[158:159], v250 offset:64
	ds_read_b64 v[160:161], v250 offset:96
	ds_read_b64 v[174:175], v250 offset:17472
	ds_read_b64 v[176:177], v250 offset:17504
	v_pk_mul_f32 v[84:85], v[84:85], v[228:229]
	v_pk_mul_f32 v[86:87], v[86:87], v[230:231]
	v_cvt_pk_bf16_f32 v88, v84, v85
	v_cvt_pk_bf16_f32 v90, v86, v87
	v_lshrrev_b32_e32 v89, 16, v88
	v_lshrrev_b32_e32 v91, 16, v90
	ds_write_b16 v253, v88 offset:4352
	ds_write_b16 v253, v89 offset:4624
	ds_write_b16 v253, v90 offset:4896
	ds_write_b16 v253, v91 offset:5168
	v_cvt_pk_bf16_f32 v186, v36, v37
	v_cvt_pk_bf16_f32 v187, v38, v39
	v_cvt_pk_bf16_f32 v188, v40, v41
	v_cvt_pk_bf16_f32 v189, v42, v43
	s_waitcnt lgkmcnt(8)
	ds_read_b64 v[162:163], v250 offset:128
	ds_read_b64 v[164:165], v250 offset:160
	ds_read_b64 v[178:179], v250 offset:17536
	ds_read_b64 v[180:181], v250 offset:17568
	s_waitcnt lgkmcnt(8)
	v_mfma_f32_16x16x32_bf16 v[76:79], v[154:157], v[186:189], v[76:79]
	v_mfma_f32_16x16x32_bf16 v[84:87], v[170:173], v[186:189], 0
	v_cvt_pk_bf16_f32 v190, v44, v45
	v_cvt_pk_bf16_f32 v191, v46, v47
	v_cvt_pk_bf16_f32 v192, v48, v49
	v_cvt_pk_bf16_f32 v193, v50, v51
	ds_read_b64 v[166:167], v250 offset:192
	ds_read_b64 v[168:169], v250 offset:224
	ds_read_b64 v[182:183], v250 offset:17600
	ds_read_b64 v[184:185], v250 offset:17632
	s_waitcnt lgkmcnt(8)
	v_mfma_f32_16x16x32_bf16 v[76:79], v[158:161], v[190:193], v[76:79]
	v_mfma_f32_16x16x32_bf16 v[84:87], v[174:177], v[190:193], v[84:87]
	v_cvt_pk_bf16_f32 v194, v52, v53
	v_cvt_pk_bf16_f32 v195, v54, v55
	v_cvt_pk_bf16_f32 v196, v56, v57
	v_cvt_pk_bf16_f32 v197, v58, v59
	ds_read_b64 v[202:203], v103 offset:34880
	ds_read_b64 v[204:205], v104 offset:34880
	ds_read_b64 v[206:207], v104 offset:37184
	ds_read_b64 v[208:209], v104 offset:39488
	s_waitcnt lgkmcnt(8)
	v_mfma_f32_16x16x32_bf16 v[76:79], v[162:165], v[194:197], v[76:79]
	v_mfma_f32_16x16x32_bf16 v[84:87], v[178:181], v[194:197], v[84:87]
	v_cvt_pk_bf16_f32 v198, v60, v61
	v_cvt_pk_bf16_f32 v199, v62, v63
	v_cvt_pk_bf16_f32 v200, v64, v65
	v_cvt_pk_bf16_f32 v201, v66, v67
	ds_read_b64 v[210:211], v103 offset:44096
	ds_read_b64 v[212:213], v103 offset:46400
	ds_read_b64 v[214:215], v103 offset:48704
	ds_read_b64 v[216:217], v103 offset:51008
	s_waitcnt lgkmcnt(8)
	v_mfma_f32_16x16x32_bf16 v[76:79], v[166:169], v[198:201], v[76:79]
	v_mfma_f32_16x16x32_bf16 v[84:87], v[182:185], v[198:201], v[84:87]
	ds_read_b128 v[220:223], v106 offset:128
	ds_read_b128 v[224:227], v107 offset:640
	ds_read_b128 v[228:231], v102 offset:128
	ds_read_b64 v[232:233], v252 offset:2560
	v_pk_mul_f32 v[36:37], v[36:37], v[238:239] op_sel_hi:[1,0]
	v_pk_mul_f32 v[38:39], v[38:39], v[238:239] op_sel_hi:[1,0]
	v_pk_mul_f32 v[40:41], v[40:41], v[238:239] op_sel_hi:[1,0]
	v_pk_mul_f32 v[42:43], v[42:43], v[238:239] op_sel_hi:[1,0]
	v_pk_mul_f32 v[44:45], v[44:45], v[238:239] op_sel_hi:[1,0]
	v_pk_mul_f32 v[46:47], v[46:47], v[238:239] op_sel_hi:[1,0]
	v_pk_mul_f32 v[48:49], v[48:49], v[238:239] op_sel_hi:[1,0]
	v_pk_mul_f32 v[50:51], v[50:51], v[238:239] op_sel_hi:[1,0]
	v_pk_mul_f32 v[52:53], v[52:53], v[238:239] op_sel_hi:[1,0]
	v_pk_mul_f32 v[54:55], v[54:55], v[238:239] op_sel_hi:[1,0]
	v_pk_mul_f32 v[56:57], v[56:57], v[238:239] op_sel_hi:[1,0]
	v_pk_mul_f32 v[58:59], v[58:59], v[238:239] op_sel_hi:[1,0]
	v_pk_mul_f32 v[60:61], v[60:61], v[238:239] op_sel_hi:[1,0]
	v_pk_mul_f32 v[62:63], v[62:63], v[238:239] op_sel_hi:[1,0]
	v_pk_mul_f32 v[64:65], v[64:65], v[238:239] op_sel_hi:[1,0]
	v_pk_mul_f32 v[66:67], v[66:67], v[238:239] op_sel_hi:[1,0]
	s_waitcnt lgkmcnt(2)
	v_cvt_pk_bf16_f32 v240, v76, v77
	v_cvt_pk_bf16_f32 v241, v78, v79
	v_pk_mul_f32 v[88:89], v[76:77], v[220:221]
	v_pk_mul_f32 v[90:91], v[78:79], v[222:223]
	v_cvt_pk_bf16_f32 v244, v88, v89
	v_cvt_pk_bf16_f32 v245, v90, v91
	v_pk_mul_f32 v[84:85], v[84:85], v[224:225]
	v_pk_mul_f32 v[86:87], v[86:87], v[226:227]
	s_waitcnt lgkmcnt(0)
; __device__ __forceinline__ void phase_gdn2(Frame& F, bool ctx_out, bool dry = false) {
;     ...
;                 for (int I = 0; I < 4; ++I) {
;                     f32x4 vn = U[I], oa = (f32x4){0.f, 0.f, 0.f, 0.f};
; #pragma unroll
;                     for (int ks = 0; ks < 4; ++ks) {
;                         const v4u sb4 = (v4u){pk2(S[2 * ks].x, S[2 * ks].y), pk2(S[2 * ks].z, S[2 * ks].w), pk2(S[2 * ks + 1].x, S[2 * ks + 1].y), pk2(S[2 * ks + 1].z, S[2 * ks + 1].w)};
;                         const hb8 fb = __builtin_bit_cast(hb8, sb4);
;                         const v2u w0 = *(const LAS v2u*)(W + (I * 16 + l15) * GS + ks * 32 + q4 * 4), w1 = *(const LAS v2u*)(W + (I * 16 + l15) * GS + ks * 32 + 16 + q4 * 4);
;                         const v2u q0 = *(const LAS v2u*)(QC + (I * 16 + l15) * GS + ks * 32 + q4 * 4), q1 = *(const LAS v2u*)(QC + (I * 16 + l15) * GS + ks * 32 + 16 + q4 * 4);
;                         const v4u fw4 = (v4u){w0.x, w0.y, w1.x, w1.y}, fq4 = (v4u){q0.x, q0.y, q1.x, q1.y};
;                         vn = MFMA16(__builtin_bit_cast(hb8, fw4), fb, vn); oa = MFMA16(__builtin_bit_cast(hb8, fq4), fb, oa); }
;                     const f32x4 ck = *(const LAS f32x4*)(s_ckd + I * 16 + q4 * 4), eg = *(const LAS f32x4*)(s_eG + I * 16 + q4 * 4), rqv = *(const LAS f32x4*)(s_rq + I * 16 + q4 * 4);
;                     const v4u vn4 = (v4u){pk2(vn.x, vn.y), pk2(vn.z, vn.w), 0u, 0u}, vp4 = (v4u){pk2(vn.x * ck.x, vn.y * ck.y), pk2(vn.z * ck.z, vn.w * ck.w), 0u, 0u};
;                     oa = oa * eg;
;                     { const v2u a0 = *(const LAS v2u*)(QKB + (I * 16 + l15) * GB + q4 * 4); const v4u fa4 = (v4u){a0.x, a0.y, 0u, 0u}; oa = MFMA16(__builtin_bit_cast(hb8, fa4), __builtin_bit_cast(hb8, vn4), oa); }
;                     oa = oa * rqv;
; #pragma unroll
;                     for (int i = 0; i < 4; ++i) O16[(I * 16 + q4 * 4 + i) * GS + vb * 16 + l15] = (bf16)f2bf(oa[i]);
;                     const float ege = s_eGend[I];
;                     const hb8 fbn = __builtin_bit_cast(hb8, vp4);
; #pragma unroll
;                     for (int kt = 0; kt < 8; ++kt) { const v2u a0 = *(const LAS v2u*)(KCT + (kt * 16 + l15) * GT + I * 16 + q4 * 4); const v4u fa4 = (v4u){a0.x, a0.y, 0u, 0u}; S[kt] = MFMA16(__builtin_bit_cast(hb8, fa4), fbn, S[kt] * ege); }
;                 }
;                 LDS_BARRIER();
	v_mfma_f32_16x16x32_bf16 v[36:39], v[202:205], v[244:247], v[36:39]
	v_mfma_f32_16x16x32_bf16 v[40:43], v[204:207], v[244:247], v[40:43]
	v_mfma_f32_16x16x32_bf16 v[84:87], v[232:235], v[240:243], v[84:87]
	v_add_u32_e32 v250, 13056, v0
	v_mfma_f32_16x16x32_bf16 v[44:47], v[206:209], v[244:247], v[44:47]
	v_mfma_f32_16x16x32_bf16 v[48:51], v[208:211], v[244:247], v[48:51]
	v_mfma_f32_16x16x32_bf16 v[52:55], v[210:213], v[244:247], v[52:55]
	v_mfma_f32_16x16x32_bf16 v[56:59], v[212:215], v[244:247], v[56:59]
	v_mfma_f32_16x16x32_bf16 v[60:63], v[214:217], v[244:247], v[60:63]
	v_mfma_f32_16x16x32_bf16 v[64:67], v[216:219], v[244:247], v[64:67]
	ds_read_b64 v[154:155], v250
	ds_read_b64 v[156:157], v250 offset:32
	ds_read_b64 v[170:171], v250 offset:17408
	ds_read_b64 v[172:173], v250 offset:17440
	ds_read_b64 v[158:159], v250 offset:64
	ds_read_b64 v[160:161], v250 offset:96
	ds_read_b64 v[174:175], v250 offset:17472
	ds_read_b64 v[176:177], v250 offset:17504
	v_pk_mul_f32 v[84:85], v[84:85], v[228:229]
	v_pk_mul_f32 v[86:87], v[86:87], v[230:231]
	v_cvt_pk_bf16_f32 v88, v84, v85
	v_cvt_pk_bf16_f32 v90, v86, v87
	v_lshrrev_b32_e32 v89, 16, v88
	v_lshrrev_b32_e32 v91, 16, v90
	ds_write_b16 v253, v88 offset:8704
	ds_write_b16 v253, v89 offset:8976
	ds_write_b16 v253, v90 offset:9248
	ds_write_b16 v253, v91 offset:9520
	v_cvt_pk_bf16_f32 v186, v36, v37
	v_cvt_pk_bf16_f32 v187, v38, v39
	v_cvt_pk_bf16_f32 v188, v40, v41
	v_cvt_pk_bf16_f32 v189, v42, v43
	s_waitcnt lgkmcnt(8)
	ds_read_b64 v[162:163], v250 offset:128
	ds_read_b64 v[164:165], v250 offset:160
	ds_read_b64 v[178:179], v250 offset:17536
	ds_read_b64 v[180:181], v250 offset:17568
	s_waitcnt lgkmcnt(8)
	v_mfma_f32_16x16x32_bf16 v[72:75], v[154:157], v[186:189], v[72:75]
	v_mfma_f32_16x16x32_bf16 v[84:87], v[170:173], v[186:189], 0
	v_cvt_pk_bf16_f32 v190, v44, v45
	v_cvt_pk_bf16_f32 v191, v46, v47
	v_cvt_pk_bf16_f32 v192, v48, v49
	v_cvt_pk_bf16_f32 v193, v50, v51
	ds_read_b64 v[166:167], v250 offset:192
	ds_read_b64 v[168:169], v250 offset:224
	ds_read_b64 v[182:183], v250 offset:17600
	ds_read_b64 v[184:185], v250 offset:17632
	s_waitcnt lgkmcnt(8)
	v_mfma_f32_16x16x32_bf16 v[72:75], v[158:161], v[190:193], v[72:75]
	v_mfma_f32_16x16x32_bf16 v[84:87], v[174:177], v[190:193], v[84:87]
	v_cvt_pk_bf16_f32 v194, v52, v53
	v_cvt_pk_bf16_f32 v195, v54, v55
	v_cvt_pk_bf16_f32 v196, v56, v57
	v_cvt_pk_bf16_f32 v197, v58, v59
	ds_read_b64 v[202:203], v103 offset:34912
	ds_read_b64 v[204:205], v104 offset:34912
	ds_read_b64 v[206:207], v104 offset:37216
	ds_read_b64 v[208:209], v104 offset:39520
	s_waitcnt lgkmcnt(8)
	v_mfma_f32_16x16x32_bf16 v[72:75], v[162:165], v[194:197], v[72:75]
	v_mfma_f32_16x16x32_bf16 v[84:87], v[178:181], v[194:197], v[84:87]
	v_cvt_pk_bf16_f32 v198, v60, v61
	v_cvt_pk_bf16_f32 v199, v62, v63
	v_cvt_pk_bf16_f32 v200, v64, v65
	v_cvt_pk_bf16_f32 v201, v66, v67
	ds_read_b64 v[210:211], v103 offset:44128
	ds_read_b64 v[212:213], v103 offset:46432
	ds_read_b64 v[214:215], v103 offset:48736
	ds_read_b64 v[216:217], v103 offset:51040
	s_waitcnt lgkmcnt(8)
	v_mfma_f32_16x16x32_bf16 v[72:75], v[166:169], v[198:201], v[72:75]
	v_mfma_f32_16x16x32_bf16 v[84:87], v[182:185], v[198:201], v[84:87]
	ds_read_b128 v[220:223], v106 offset:192
	ds_read_b128 v[224:227], v107 offset:704
	ds_read_b128 v[228:231], v102 offset:192
	ds_read_b64 v[232:233], v252 offset:3840
	v_pk_mul_f32 v[36:37], v[36:37], v[238:239] op_sel:[0,1]
	v_pk_mul_f32 v[38:39], v[38:39], v[238:239] op_sel:[0,1]
	v_pk_mul_f32 v[40:41], v[40:41], v[238:239] op_sel:[0,1]
	v_pk_mul_f32 v[42:43], v[42:43], v[238:239] op_sel:[0,1]
	v_pk_mul_f32 v[44:45], v[44:45], v[238:239] op_sel:[0,1]
	v_pk_mul_f32 v[46:47], v[46:47], v[238:239] op_sel:[0,1]
	v_pk_mul_f32 v[48:49], v[48:49], v[238:239] op_sel:[0,1]
	v_pk_mul_f32 v[50:51], v[50:51], v[238:239] op_sel:[0,1]
	v_pk_mul_f32 v[52:53], v[52:53], v[238:239] op_sel:[0,1]
	v_pk_mul_f32 v[54:55], v[54:55], v[238:239] op_sel:[0,1]
	v_pk_mul_f32 v[56:57], v[56:57], v[238:239] op_sel:[0,1]
	v_pk_mul_f32 v[58:59], v[58:59], v[238:239] op_sel:[0,1]
	v_pk_mul_f32 v[60:61], v[60:61], v[238:239] op_sel:[0,1]
	v_pk_mul_f32 v[62:63], v[62:63], v[238:239] op_sel:[0,1]
	v_pk_mul_f32 v[64:65], v[64:65], v[238:239] op_sel:[0,1]
	v_pk_mul_f32 v[66:67], v[66:67], v[238:239] op_sel:[0,1]
	s_waitcnt lgkmcnt(2)
	v_cvt_pk_bf16_f32 v240, v72, v73
	v_cvt_pk_bf16_f32 v241, v74, v75
	v_pk_mul_f32 v[88:89], v[72:73], v[220:221]
	v_pk_mul_f32 v[90:91], v[74:75], v[222:223]
	v_cvt_pk_bf16_f32 v244, v88, v89
	v_cvt_pk_bf16_f32 v245, v90, v91
	v_pk_mul_f32 v[84:85], v[84:85], v[224:225]
	v_pk_mul_f32 v[86:87], v[86:87], v[226:227]
	s_waitcnt lgkmcnt(0)
	v_mfma_f32_16x16x32_bf16 v[36:39], v[202:205], v[244:247], v[36:39]
	v_mfma_f32_16x16x32_bf16 v[40:43], v[204:207], v[244:247], v[40:43]
	v_mfma_f32_16x16x32_bf16 v[84:87], v[232:235], v[240:243], v[84:87]
	v_mfma_f32_16x16x32_bf16 v[44:47], v[206:209], v[244:247], v[44:47]
	v_mfma_f32_16x16x32_bf16 v[48:51], v[208:211], v[244:247], v[48:51]
	v_mfma_f32_16x16x32_bf16 v[52:55], v[210:213], v[244:247], v[52:55]
	v_mfma_f32_16x16x32_bf16 v[56:59], v[212:215], v[244:247], v[56:59]
	v_mfma_f32_16x16x32_bf16 v[60:63], v[214:217], v[244:247], v[60:63]
	v_mfma_f32_16x16x32_bf16 v[64:67], v[216:219], v[244:247], v[64:67]
	s_nop 1
	v_pk_mul_f32 v[84:85], v[84:85], v[228:229]
	v_pk_mul_f32 v[86:87], v[86:87], v[230:231]
	v_cvt_pk_bf16_f32 v88, v84, v85
	v_cvt_pk_bf16_f32 v90, v86, v87
	v_lshrrev_b32_e32 v89, 16, v88
	v_lshrrev_b32_e32 v91, 16, v90
	ds_write_b16 v253, v88 offset:13056
	ds_write_b16 v253, v89 offset:13328
	ds_write_b16 v253, v90 offset:13600
	ds_write_b16 v253, v91 offset:13872
	s_waitcnt lgkmcnt(0)
	s_barrier
	s_waitcnt lgkmcnt(0)
	s_cbranch_scc1 .LBB0_1021

; #define LAS __attribute__((address_space(3)))
; #define GDN_REV(x_) x_ = (v4u){__builtin_amdgcn_alignbit(x_.w, x_.w, 16), __builtin_amdgcn_alignbit(x_.z, x_.z, 16), __builtin_amdgcn_alignbit(x_.y, x_.y, 16), __builtin_amdgcn_alignbit(x_.x, x_.x, 16)}
; __device__ __forceinline__ void phase_gdn2(Frame& F, bool ctx_out, bool dry = false) {
;     ...
;                     const int pcs = tid & 7, tp = d ? 56 - pcs * 8 : pcs * 8;
;                     v4u x4 = rawp[4], x5 = rawp[5], x6 = rawp[6], x7 = rawp[7];
;                     if (d) {
;     ...
;                         GDN_REV(x4); GDN_REV(x5); GDN_REV(x6); GDN_REV(x7);
;     ...
;                     }
;                     const int kch = tid >> 3;
;                     *(LAS v4u*)(KCT + kch * GT + tp) = x4; *(LAS v4u*)(KCT + (kch + 64) * GT + tp) = x5;
;                     const int vch = 2 * r0 + ((tid >> 3) & 1);
;                     *(LAS v4u*)(VT + vch * GT + tp) = x6; *(LAS v4u*)(VT + (vch + 64) * GT + tp) = x7;
;                 }
;                 if (st + 1 < (TCX + TL) / 64) GDN_PREFETCH(st + 1);
.LBB0_970:
	v_and_b32_e32 v102, 56, v0
	v_bitop3_b32 v0, v0, 56, v0 bitop3:0xc
	v_cndmask_b32_e64 v102, v0, v102, s[28:29]
	v_ashrrev_i32_e32 v0, 3, v100
	v_mul_lo_u32 v103, v0, s10
	v_lshlrev_b32_e32 v102, 1, v102
	v_add3_u32 v103, 0, v103, v102
	ds_write_b128 v103, v[84:87] offset:34816
	ds_write_b128 v103, v[88:91] offset:44032
	v_and_b32_e32 v84, 1, v0
	s_add_i32 s52, s56, -1
	v_lshl_or_b32 v84, v1, 1, v84
	v_mul_lo_u32 v84, v84, s10
	s_cmpk_lg_i32 s3, 0x8c0
	v_add3_u32 v84, 0, v84, v102
	s_cselect_b64 s[50:51], -1, 0
	s_cmpk_eq_i32 s3, 0x8c0
	v_cmp_lt_i32_e64 s[14:15], s97, v100
	v_add_u32_e32 v85, 0xd800, v84
	ds_write_b128 v84, v[92:95] offset:55296
	ds_write_b128 v85, v[96:99] offset:9216
	s_cbranch_scc1 .LBB0_974
	s_add_i32 s30, s3, 64
	s_add_i32 s31, s3, 0xffffff40
	s_cmp_lt_u32 s52, 3
	s_cselect_b32 s76, s30, s31
	s_cselect_b32 s30, 0xc0, s57
	s_cselect_b32 s53, s54, s2
	s_sub_i32 s81, s30, s76
	s_and_b64 s[30:31], s[28:29], exec
	s_cselect_b32 s81, s76, s81
	s_add_i32 s82, s81, s53
	s_mul_i32 s31, s82, 0x6200
	s_mul_hi_i32 s30, s82, 0x6200
	s_add_u32 s83, s34, s31
	s_addc_u32 s86, s35, s30
	v_mul_lo_u32 v1, v1, s11
	s_add_u32 s30, s83, s55
	v_or_b32_e32 v1, v1, v101
	s_addc_u32 s31, s86, 0
	v_lshlrev_b32_e32 v1, 1, v1
	v_add_u32_e32 v32, 0xc4000, v1
	global_load_dwordx4 v[4:7], v1, s[30:31]
	global_load_dwordx4 v[8:11], v32, s[30:31]
	s_add_u32 s30, s30, 0x1000
	s_addc_u32 s31, s31, 0
	global_load_dwordx4 v[12:15], v1, s[30:31]
	global_load_dwordx4 v[16:19], v32, s[30:31]
	s_ashr_i32 s30, s82, 6
	s_ashr_i32 s31, s30, 31
	s_lshl_b64 s[30:31], s[30:31], 18
	s_add_u32 s30, s5, s30
	s_addc_u32 s31, s6, s31
	v_lshlrev_b32_e32 v20, 4, v100
	v_mov_b32_e32 v21, v2
	v_lshl_add_u64 v[24:25], s[30:31], 0, v[20:21]
	v_add_co_u32_e32 v24, vcc, s92, v24
	global_load_dwordx4 v[20:23], v20, s[30:31]
	s_nop 0
	v_addc_co_u32_e32 v25, vcc, 0, v25, vcc
	global_load_dwordx4 v[24:27], v[24:25], off
	s_add_u32 s30, s83, s61
	s_addc_u32 s31, s86, 0
	s_add_u32 s30, s30, 0x2000
	s_addc_u32 s31, s31, 0
	global_load_dwordx4 v[28:31], v1, s[30:31]
	s_nop 0
	global_load_dwordx4 v[32:35], v32, s[30:31]
	s_and_saveexec_b64 s[30:31], s[14:15]
	s_cbranch_execz .LBB0_973
	v_add_u32_e32 v1, s76, v100
	v_sub_u32_e32 v84, s81, v100
	v_add_u32_e32 v84, 0x1ff, v84
	v_add_u32_e32 v1, 0xfffffe40, v1
	v_cndmask_b32_e64 v1, v84, v1, s[28:29]
	v_add_u32_e32 v1, s53, v1
	v_mov_b64_e32 v[84:85], s[34:35]
	v_mad_i64_i32 v[84:85], s[14:15], v1, s90, v[84:85]
	v_lshl_add_u64 v[84:85], v[84:85], 0, s[36:37]
	v_lshl_add_u64 v[84:85], s[18:19], 1, v[84:85]
	v_lshl_add_u64 v[86:87], v[84:85], 0, s[48:49]
	v_add_co_u32_e32 v84, vcc, 0x6000, v84
	s_nop 1
	v_addc_co_u32_e32 v85, vcc, 0, v85, vcc
	global_load_ushort v136, v[84:85], off
	global_load_ushort v135, v[86:87], off offset:64

; #define GAS __attribute__((address_space(1)))
; __device__ __forceinline__ void phase_hg2(Frame& F, int j, bool ctx_out, bool dry = false) {
;     FRAME_TID(F);
;     gb P = (gb)(F.ws + WS_P); gb OF = (gb)(F.ws + WS_O);
;     gcf lbl = F.in[I_HGLB]; gcf ng = F.in[I_HGNG] + j * 128;
;     LAS bf16* Qt = (LAS bf16*)(F.lds + HG_QT); LAS bf16* Kt = (LAS bf16*)(F.lds + HG_KT); LAS bf16* KtT = (LAS bf16*)(F.lds + HG_KTT); LAS bf16* VT = (LAS bf16*)(F.lds + HG_VT);
;     LAS bf16* ATT = (LAS bf16*)(F.lds + HG_ATT); LAS bf16* SB = (LAS bf16*)(F.lds + HG_SB);
;     LAS float* er = (LAS float*)(F.lds + HG_ER); LAS float* eend = (LAS float*)(F.lds + HG_EEND); LAS float* segs = (LAS float*)(F.lds + HG_SEG);
;     LAS float* s_ng = (LAS float*)(F.lds + 131072);
;     LAS float* O32 = (LAS float*)(F.lds + HG_QT);
;     const int c2_ = F.tid & 63, seg_ = F.tid >> 6;
;     const int l15_ = F.lane & 15, q4_ = F.lane >> 4, vb = F.wave;
;     const int rt = F.tid >> 3, g8 = F.tid & 7;
;     for (int item = blockIdx.x; item < NB * 16; item += F.G) {
;         const int b = item >> 4, h = item & 15;
;         if (F.tid < 128) s_ng[F.tid] = ng[F.tid];
;         for (int d = 0; d < 2; ++d) {
;             float lb0, lb1;
;             { const int cc = 2 * c2_;
;               const float a0 = lbl[(0 * 2 + d) * DM + h * 128 + cc], a1 = lbl[(1 * 2 + d) * DM + h * 128 + cc], b0 = lbl[(0 * 2 + d) * DM + h * 128 + cc + 1], b1 = lbl[(1 * 2 + d) * DM + h * 128 + cc + 1];
;               const float mx = fmaxf(a0, a1), e0 = __expf(a0 - mx), e1 = __expf(a1 - mx), my = fmaxf(b0, b1), f0 = __expf(b0 - my), f1 = __expf(b1 - my);
;               lb0 = (j == 0) ? 0.f : e1 / (e0 + e1); lb1 = (j == 0) ? 0.f : f1 / (f0 + f1); }
;             f32x4 S[8];
; #pragma unroll
;             for (int kt = 0; kt < 8; ++kt) S[kt] = (f32x4){0.f, 0.f, 0.f, 0.f};
;             unsigned rq[8], rf[8], rv[8];
;             {
;                 gcb pr = P + h * 128 + 2 * c2_;
; #pragma unroll
;                 for (int i = 0; i < 8; ++i) { const size_t ro = (size_t)hg_row(b, d, seg_ * 8 + i) * HG_N; rq[i] = *(GAS const unsigned*)(pr + ro); rv[i] = *(GAS const unsigned*)(pr + ro + DM); rf[i] = *(GAS const unsigned*)(pr + ro + (2 + d) * DM); }
;             }
; #pragma unroll 1
;             for (int ch = 0; ch < (TCX + TL) / 64; ++ch) {
;                 const int s0 = ch * 64;
.LBB0_2336:
	s_waitcnt lgkmcnt(0)
	s_add_u32 s82, s70, 0x41900000
	s_addc_u32 s83, s71, 0
	s_cmp_gt_i32 s52, 27
	s_cselect_b64 s[0:1], -1, 0
	s_cmp_lt_i32 s53, 28
	s_cselect_b64 s[2:3], -1, 0
	s_or_b64 s[0:1], s[0:1], s[2:3]
	s_and_b64 vcc, exec, s[0:1]
	s_cbranch_vccnz .LBB0_2431
	s_cmpk_gt_i32 s73, 0xff
	v_mbcnt_lo_u32_b32 v0, -1, 0
	v_mbcnt_hi_u32_b32 v0, -1, v0
	s_cbranch_scc1 .LBB0_2381
	s_load_dwordx2 s[2:3], s[94:95], 0xd8
	v_readlane_b32 s5, v254, 57
	s_mov_b32 s7, 0
	v_readlane_b32 s4, v254, 0
	v_and_b32_e32 v101, 63, v0
	s_waitcnt lgkmcnt(0)
	s_add_u32 s0, s2, 0xa700000
	v_writelane_b32 v255, s0, 10
	s_addc_u32 s0, s3, 0
	s_cmpk_lt_u32 s5, 0x100
	v_writelane_b32 v255, s0, 11
	s_cselect_b64 s[76:77], -1, 0
	s_lshl_b32 s1, s33, 9
	v_writelane_b32 v255, s6, 15
	s_add_i32 s94, s1, 0
	s_lshl_b32 s34, s33, 4
	v_add_u32_e32 v2, s4, v0
	v_writelane_b32 v255, s7, 16
	s_add_i32 s12, s94, 0x1ec00
	s_lshl_b32 s1, s33, 3
	s_add_i32 s35, s34, 0
	v_ashrrev_i32_e32 v130, 3, v2
	v_writelane_b32 v255, s1, 13
	s_add_u32 s1, s2, 0xa704000
	v_and_b32_e32 v132, -8, v130
	s_movk_i32 s0, 0x100
	v_writelane_b32 v255, s1, 12
	s_addc_u32 s1, s3, 0
	v_writelane_b32 v255, s1, 29
	v_cmp_gt_i32_e64 s[6:7], s0, v132
	v_or_b32_e32 v136, 1, v132
	v_or_b32_e32 v140, 2, v132
	v_writelane_b32 v255, s6, 17
	v_or_b32_e32 v144, 3, v132
	v_or_b32_e32 v148, 4, v132
	v_writelane_b32 v255, s7, 18
	v_cmp_gt_i32_e64 s[6:7], s0, v136
	v_or_b32_e32 v152, 5, v132
	s_cmp_lt_u32 s5, 64
	v_writelane_b32 v255, s6, 19
	v_or_b32_e32 v156, 6, v132
	s_cselect_b64 s[2:3], -1, 0
	v_writelane_b32 v255, s7, 20
	v_cmp_gt_i32_e64 s[6:7], s0, v140
	s_add_i32 s72, s4, 0
	v_or_b32_e32 v160, 7, v130
	v_writelane_b32 v255, s6, 21
	s_cmpk_lt_u32 s5, 0x80
	s_cselect_b64 s[20:21], -1, 0
	v_writelane_b32 v255, s7, 22
	v_cmp_gt_i32_e64 s[6:7], s0, v144
	s_cmpk_lt_u32 s5, 0xc0
	s_cselect_b64 s[22:23], -1, 0
	v_writelane_b32 v255, s6, 23
	s_cmpk_gt_u32 s5, 0x13f
	s_cselect_b64 s[24:25], -1, 0
	v_writelane_b32 v255, s7, 24
	v_cmp_gt_i32_e64 s[6:7], s0, v148
	s_cmpk_gt_u32 s5, 0x17f
	s_cselect_b64 s[26:27], -1, 0
	v_writelane_b32 v255, s6, 25
	s_cmpk_gt_u32 s5, 0x1bf
	s_cselect_b64 s[28:29], -1, 0
	v_writelane_b32 v255, s7, 26
	v_cmp_gt_i32_e64 s[6:7], s0, v152
	s_cmpk_gt_u32 s5, 0x1ff
	s_cselect_b64 s[30:31], -1, 0
	v_writelane_b32 v255, s6, 27
	v_readlane_b32 s36, v254, 21
	v_lshlrev_b32_e32 v100, 1, v101
	v_writelane_b32 v255, s7, 28
	v_cmp_gt_i32_e64 s[6:7], s0, v156
	v_cmp_gt_i32_e64 s[0:1], s0, v160
	v_mov_b32_e32 v103, 0
	v_writelane_b32 v255, s6, 31
	v_ashrrev_i32_e32 v3, 31, v2
	v_readlane_b32 s37, v254, 22
	v_writelane_b32 v255, s7, 32
	v_writelane_b32 v255, s0, 5
	v_readlane_b32 s38, v254, 23
	v_readlane_b32 s39, v254, 24
	v_writelane_b32 v255, s1, 6
	s_movk_i32 s0, 0x80
	v_cmp_gt_i32_e64 s[0:1], s0, v2
	v_readlane_b32 s40, v254, 25
	v_readlane_b32 s41, v254, 26
	v_writelane_b32 v255, s0, 33
	v_readlane_b32 s42, v254, 27
	v_readlane_b32 s43, v254, 28
	v_writelane_b32 v255, s1, 34
	s_add_i32 s0, 0, 0x20000
	v_lshl_add_u32 v164, v2, 2, s0
	s_lshl_b32 s0, s33, 1
	s_lshr_b32 s1, s5, 7
	s_and_b32 s0, s0, 2
	s_cmp_ge_u32 s0, s1
	s_cselect_b64 s[80:81], -1, 0
	s_lshl_b32 s73, s1, 4
	s_lshl_b32 s4, s0, 4
	s_or_b32 s0, s0, 1
	s_cmp_ge_u32 s0, s1
	s_cselect_b64 s[84:85], -1, 0
	s_lshl_b32 s5, s0, 4
	s_mul_i32 s0, s33, 0x880
	v_readlane_b32 s44, v254, 29
	v_readlane_b32 s45, v254, 30
	v_readlane_b32 s46, v254, 31
	v_readlane_b32 s47, v254, 32
	v_readlane_b32 s48, v254, 33
	v_readlane_b32 s49, v254, 34
	v_readlane_b32 s50, v254, 35
	v_readlane_b32 s51, v254, 36
	s_add_i32 s6, s0, 0
	v_readlane_b32 s0, v255, 2
	v_writelane_b32 v254, s82, 37
	v_and_b32_e32 v128, 15, v0
	v_ashrrev_i32_e32 v129, 4, v0
	v_and_b32_e32 v131, 7, v0
	v_sub_u32_e32 v133, 0x8ff, v132
	v_add_u32_e32 v134, 0xffffff00, v132
	v_sub_u32_e32 v135, 0xff, v132
	v_sub_u32_e32 v137, 0x8ff, v136
	v_add_u32_e32 v138, 0xffffff01, v132
	v_sub_u32_e32 v139, 0xff, v136
	v_sub_u32_e32 v141, 0x8ff, v140
	v_add_u32_e32 v142, 0xffffff02, v132
	v_sub_u32_e32 v143, 0xff, v140
	v_sub_u32_e32 v145, 0x8ff, v144
	v_add_u32_e32 v146, 0xffffff03, v132
	v_sub_u32_e32 v147, 0xff, v144
	v_sub_u32_e32 v149, 0x8ff, v148
	v_add_u32_e32 v150, 0xffffff04, v132
	v_sub_u32_e32 v151, 0xff, v148
	v_sub_u32_e32 v153, 0x8ff, v152
	v_add_u32_e32 v154, 0xffffff05, v132
	v_sub_u32_e32 v155, 0xff, v152
	v_sub_u32_e32 v157, 0x8ff, v156
	v_add_u32_e32 v158, 0xffffff06, v132
	v_sub_u32_e32 v159, 0xff, v156
	v_sub_u32_e32 v161, 0x8ff, v160
	v_add_u32_e32 v162, 0xffffff00, v160
	v_sub_u32_e32 v163, 0xff, v160
	v_lshl_add_u64 v[104:105], v[2:3], 2, s[40:41]
	v_lshlrev_b32_e32 v106, 1, v100
	v_mov_b32_e32 v107, v103
	s_mov_b32 s9, 0xffff0000
	s_mov_b32 s10, 0xbfb8aa3b
	s_mov_b32 s11, 0xffff
	s_movk_i32 s13, 0x110
	s_movk_i32 s14, 0xa0
	s_add_i32 s15, 0, 0x13000
	v_mov_b32_e32 v165, 0x358637bd
	s_mov_b32 s7, s0
	v_writelane_b32 v254, s83, 38
	s_branch .LBB0_2340

; #define LAS __attribute__((address_space(3)))
; __device__ __forceinline__ void phase_hg2(Frame& F, int j, bool ctx_out, bool dry = false) {
;     ...
;                 float m0 = 1.f, m1 = 1.f, er0 = 1.f, er1 = 1.f, en0 = 1.f, en1 = 1.f;
; #pragma unroll
;                 for (int sg = 0; sg < 8; ++sg) { const v2f g = *(const LAS v2f*)(segs + sg * 128 + 2 * c2);
;                     if (sg < 4) { er0 = fmaxf(er0 * g.x, 1e-30f); er1 = fmaxf(er1 * g.y, 1e-30f); } else { en0 = fmaxf(en0 * g.x, 1e-30f); en1 = fmaxf(en1 * g.y, 1e-30f); }
;                     const bool inm = (seg >= 4) ? (sg >= 4 && sg < seg) : (sg > seg && sg < 4);
;                     if (inm) { m0 = fmaxf(m0 * g.x, 1e-30f); m1 = fmaxf(m1 * g.y, 1e-30f); } }
;                 if (seg == 0) { *(LAS v2f*)(er + 2 * c2) = (v2f){er0, er1}; *(LAS v2f*)(eend + 2 * c2) = (v2f){en0, en1}; }
;                 {
;                     unsigned k0[8], k1[8];
;                     const v2f m2 = (v2f){m0, m1};
;     ...
;                     if (seg >= 4) { HG_PASS2(small_, big_) } else { HG_PASS2(big_, small_) }
;     ...
;                     *(LAS v4u*)(KtT + (2 * c2) * HTS + seg * 8) = (v4u){k0[0] | (k0[1] << 16), k0[2] | (k0[3] << 16), k0[4] | (k0[5] << 16), k0[6] | (k0[7] << 16)};
;                     *(LAS v4u*)(KtT + (2 * c2 + 1) * HTS + seg * 8) = (v4u){k1[0] | (k1[1] << 16), k1[2] | (k1[3] << 16), k1[4] | (k1[5] << 16), k1[6] | (k1[7] << 16)};
;                 }
.LBB0_2361:
	s_waitcnt lgkmcnt(3)
	v_max_f32_e32 v24, v24, v24
	v_max_f32_e32 v25, v25, v25
	v_max_f32_e32 v24, 0xda24260, v24
	v_max_f32_e32 v25, 0xda24260, v25
	v_cndmask_b32_e64 v25, 1.0, v25, s[2:3]
	v_cndmask_b32_e64 v24, 1.0, v24, s[2:3]
	v_mul_f32_e32 v24, v26, v24
	v_mul_f32_e32 v25, v27, v25
	v_max_f32_e32 v24, 0xda24260, v24
	v_max_f32_e32 v25, 0xda24260, v25
	v_cndmask_b32_e64 v25, 1.0, v25, s[20:21]
	v_cndmask_b32_e64 v24, 1.0, v24, s[20:21]
	s_waitcnt lgkmcnt(2)
	v_mul_f32_e32 v20, v20, v24
	v_mul_f32_e32 v21, v21, v25
	v_max_f32_e32 v20, 0xda24260, v20
	v_max_f32_e32 v21, 0xda24260, v21
	v_cndmask_b32_e64 v21, 1.0, v21, s[22:23]
	v_cndmask_b32_e64 v20, 1.0, v20, s[22:23]
	v_mul_f32_e32 v22, v22, v20
	v_mul_f32_e32 v23, v23, v21
	v_max_f32_e32 v22, 0xda24260, v22
	v_max_f32_e32 v23, 0xda24260, v23
	v_cndmask_b32_e64 v21, v21, v23, s[24:25]
	v_cndmask_b32_e64 v20, v20, v22, s[24:25]
	s_waitcnt lgkmcnt(1)
	v_mul_f32_e32 v16, v16, v20
	v_mul_f32_e32 v17, v17, v21
	v_max_f32_e32 v16, 0xda24260, v16
	v_max_f32_e32 v17, 0xda24260, v17
	v_cndmask_b32_e64 v17, v21, v17, s[26:27]
	v_cndmask_b32_e64 v16, v20, v16, s[26:27]
	v_mul_f32_e32 v18, v18, v16
	v_mul_f32_e32 v19, v19, v17
	v_max_f32_e32 v18, 0xda24260, v18
	v_max_f32_e32 v19, 0xda24260, v19
	v_cndmask_b32_e64 v17, v17, v19, s[28:29]
	v_cndmask_b32_e64 v16, v16, v18, s[28:29]
	s_waitcnt lgkmcnt(0)
	v_mul_f32_e32 v18, v122, v16
	v_mul_f32_e32 v19, v123, v17
	v_max_f32_e32 v18, 0xda24260, v18
	v_max_f32_e32 v19, 0xda24260, v19
	v_cndmask_b32_e64 v17, v17, v19, s[30:31]
	v_cndmask_b32_e64 v16, v16, v18, s[30:31]
	v_cndmask_b32_e64 v19, v43, v45, s[44:45]
	v_cndmask_b32_e64 v18, v42, v44, s[42:43]
	v_pk_mul_f32 v[18:19], v[112:113], v[18:19]
	v_lshl_add_u32 v204, v201, 1, s6
	v_cvt_pk_bf16_f32 v20, v18, v19
	v_cndmask_b32_e64 v19, v47, v49, s[48:49]
	v_cndmask_b32_e64 v18, v46, v48, s[46:47]
	v_pk_mul_f32 v[18:19], v[112:113], v[18:19]
	v_lshlrev_b32_e32 v26, 16, v126
	v_cvt_pk_bf16_f32 v21, v18, v19
	v_cndmask_b32_e64 v19, v51, v85, s[52:53]
	v_cndmask_b32_e64 v18, v50, v84, s[50:51]
	v_pk_mul_f32 v[18:19], v[112:113], v[18:19]
	v_and_b32_e32 v27, 0xffff0000, v126
	v_cvt_pk_bf16_f32 v46, v18, v19
	v_cndmask_b32_e64 v19, v87, v89, s[56:57]
	v_cndmask_b32_e64 v18, v86, v88, s[54:55]
	v_pk_mul_f32 v[18:19], v[112:113], v[18:19]
	v_lshlrev_b32_e32 v48, 16, v125
	v_cvt_pk_bf16_f32 v47, v18, v19
	v_cndmask_b32_e64 v19, v91, v93, s[60:61]
	v_cndmask_b32_e64 v18, v90, v92, s[58:59]
	v_pk_mul_f32 v[18:19], v[112:113], v[18:19]
	v_and_b32_e32 v49, 0xffff0000, v125
	v_cvt_pk_bf16_f32 v50, v18, v19
	v_cndmask_b32_e64 v19, v95, v97, s[66:67]
	v_cndmask_b32_e64 v18, v94, v96, s[64:65]
	v_pk_mul_f32 v[18:19], v[112:113], v[18:19]
	v_lshlrev_b32_e32 v84, 16, v21
	v_cvt_pk_bf16_f32 v122, v18, v19
	v_cndmask_b32_e64 v19, v99, v115, s[70:71]
	v_cndmask_b32_e64 v18, v98, v114, s[68:69]
	v_pk_mul_f32 v[18:19], v[112:113], v[18:19]
	v_and_b32_e32 v85, 0xffff0000, v21
	v_cvt_pk_bf16_f32 v123, v18, v19
	v_pk_mul_f32 v[18:19], v[40:41], v[16:17]
	v_lshlrev_b32_e32 v40, 16, v20
	v_max_f32_e32 v22, 0xda24260, v18
	v_max_f32_e32 v23, 0xda24260, v19
	v_pk_mul_f32 v[18:19], v[120:121], v[16:17]
	v_rcp_f32_e32 v24, v22
	v_max_f32_e32 v42, 0xda24260, v18
	v_max_f32_e32 v43, 0xda24260, v19
	v_pk_mul_f32 v[18:19], v[118:119], v[16:17]
	v_rcp_f32_e32 v25, v23
	v_max_f32_e32 v86, 0xda24260, v18
	v_max_f32_e32 v87, 0xda24260, v19
	v_pk_mul_f32 v[18:19], v[116:117], v[16:17]
	v_rcp_f32_e32 v44, v42
	v_max_f32_e32 v98, 0xda24260, v18
	v_max_f32_e32 v99, 0xda24260, v19
	v_rcp_f32_e32 v45, v43
	v_rcp_f32_e32 v88, v86
	v_rcp_f32_e32 v89, v87
	v_rcp_f32_e32 v114, v98
	v_rcp_f32_e32 v115, v99
	v_and_b32_e32 v41, 0xffff0000, v20
	v_lshlrev_b32_e32 v90, 16, v124
	v_and_b32_e32 v91, 0xffff0000, v124
	v_lshlrev_b32_e32 v92, 16, v46
	v_and_b32_e32 v93, 0xffff0000, v46
	v_lshlrev_b32_e32 v116, 16, v198
	v_and_b32_e32 v117, 0xffff0000, v198
	v_lshlrev_b32_e32 v118, 16, v47
	v_and_b32_e32 v119, 0xffff0000, v47
	s_mov_b64 s[42:43], -1
	s_and_b64 vcc, exec, s[62:63]
	v_lshlrev_b32_e32 v96, 16, v127
	v_and_b32_e32 v97, 0xffff0000, v127
	v_lshlrev_b32_e32 v94, 16, v50
	v_and_b32_e32 v95, 0xffff0000, v50
	v_lshlrev_b32_e32 v50, 16, v197
	v_and_b32_e32 v51, 0xffff0000, v197
	v_lshlrev_b32_e32 v46, 16, v122
	v_and_b32_e32 v47, 0xffff0000, v122
	v_lshlrev_b32_e32 v18, 16, v199
	v_and_b32_e32 v19, 0xffff0000, v199
	v_lshlrev_b32_e32 v20, 16, v123
	v_and_b32_e32 v21, 0xffff0000, v123
	v_add_u32_e32 v205, 0x4800, v204
	v_add_u32_e32 v198, 0x400, v204
	v_add_u32_e32 v197, 0x4c00, v204
	s_cbranch_vccnz .LBB0_2363
	v_pk_mul_f32 v[120:121], v[24:25], v[26:27]
	v_pk_mul_f32 v[122:123], v[22:23], v[40:41]
	v_cvt_pk_bf16_f32 v124, v120, v121
	v_pk_mul_f32 v[120:121], v[44:45], v[48:49]
	v_cvt_pk_bf16_f32 v201, v122, v123
	v_cvt_pk_bf16_f32 v120, v120, v121
	ds_write2_b32 v204, v124, v120 offset1:68
	v_pk_mul_f32 v[120:121], v[88:89], v[90:91]
	v_pk_mul_f32 v[122:123], v[42:43], v[84:85]
	v_cvt_pk_bf16_f32 v124, v120, v121
	v_pk_mul_f32 v[120:121], v[114:115], v[116:117]
	v_cvt_pk_bf16_f32 v199, v122, v123
	v_cvt_pk_bf16_f32 v120, v120, v121
	v_pk_mul_f32 v[122:123], v[86:87], v[92:93]
	ds_write2_b32 v204, v124, v120 offset0:136 offset1:204
	v_pk_mul_f32 v[120:121], v[36:37], v[16:17]
	v_cvt_pk_bf16_f32 v202, v122, v123
	v_pk_mul_f32 v[122:123], v[98:99], v[118:119]
	v_max_f32_e32 v120, 0xda24260, v120
	v_max_f32_e32 v121, 0xda24260, v121
	v_cvt_pk_bf16_f32 v203, v122, v123
	v_rcp_f32_e32 v122, v120
	v_rcp_f32_e32 v123, v121
	v_pk_mul_f32 v[120:121], v[120:121], v[94:95]
	s_mov_b64 s[42:43], 0
	v_cvt_pk_bf16_f32 v206, v120, v121
	v_pk_mul_f32 v[120:121], v[34:35], v[16:17]
	v_pk_mul_f32 v[122:123], v[122:123], v[96:97]
	v_max_f32_e32 v120, 0xda24260, v120
	v_max_f32_e32 v121, 0xda24260, v121
	v_cvt_pk_bf16_f32 v124, v122, v123
	v_rcp_f32_e32 v122, v120
	v_rcp_f32_e32 v123, v121
	v_pk_mul_f32 v[120:121], v[120:121], v[46:47]
	ds_write2_b32 v205, v201, v199 offset1:68
	v_cvt_pk_bf16_f32 v207, v120, v121
	v_pk_mul_f32 v[122:123], v[122:123], v[50:51]
	v_pk_mul_f32 v[120:121], v[32:33], v[16:17]
	v_cvt_pk_bf16_f32 v122, v122, v123
	ds_write2_b32 v198, v124, v122 offset0:16 offset1:84
	v_max_f32_e32 v122, 0xda24260, v120
	v_max_f32_e32 v123, 0xda24260, v121
	v_pk_mul_f32 v[124:125], v[38:39], v[16:17]
	v_rcp_f32_e32 v120, v122
	v_rcp_f32_e32 v121, v123
	v_max_f32_e32 v124, 0xda24260, v124
	v_max_f32_e32 v125, 0xda24260, v125
	v_rcp_f32_e32 v126, v124
	v_rcp_f32_e32 v127, v125
	v_pk_mul_f32 v[120:121], v[120:121], v[18:19]
	v_pk_mul_f32 v[122:123], v[122:123], v[20:21]
	ds_write2_b32 v205, v202, v203 offset0:136 offset1:204
	ds_write2_b32 v197, v206, v207 offset0:16 offset1:84
; #define LAS __attribute__((address_space(3)))
; #define LDS_BARRIER() do { asm volatile("s_waitcnt lgkmcnt(0)" ::: "memory"); __builtin_amdgcn_s_barrier(); asm volatile("" ::: "memory"); } while (0)
; #define MFMA16(a, b, c) __builtin_amdgcn_mfma_f32_16x16x32_bf16((a), (b), (c), 0, 0, 0)
; __device__ __forceinline__ void phase_hg2(Frame& F, int j, bool ctx_out, bool dry = false) {
;     ...
;                     if (seg >= 4) { HG_PASS2(small_, big_) } else { HG_PASS2(big_, small_) }
;     ...
;                     *(LAS v4u*)(KtT + (2 * c2) * HTS + seg * 8) = (v4u){k0[0] | (k0[1] << 16), k0[2] | (k0[3] << 16), k0[4] | (k0[5] << 16), k0[6] | (k0[7] << 16)};
;                     *(LAS v4u*)(KtT + (2 * c2 + 1) * HTS + seg * 8) = (v4u){k1[0] | (k1[1] << 16), k1[2] | (k1[3] << 16), k1[4] | (k1[5] << 16), k1[6] | (k1[7] << 16)};
;                 }
;                 LDS_BARRIER();
; #pragma unroll
;                 for (int kt = 0; kt < 8; ++kt) { const f32x4 e4 = *(const LAS f32x4*)(er + kt * 16 + q4 * 4); S[kt] = S[kt] * e4; }
; #pragma unroll
;                 for (int tl = 0; tl < 2; ++tl) { const int id = F.wave * 2 + tl, st = id >> 2, tt = id & 3;
;                     f32x4 a = (f32x4){0.f, 0.f, 0.f, 0.f};
;                     if (tt >= st) {
; #pragma unroll
;                         for (int ks = 0; ks < 4; ++ks) { const hb8 fa = *(const LAS hb8*)(Kt + (st * 16 + l15) * HQS + ks * 32 + q4 * 8), fb = *(const LAS hb8*)(Qt + (tt * 16 + l15) * HQS + ks * 32 + q4 * 8);
;                             a = MFMA16(fa, fb, a); }
.LBB0_2363:
	s_andn2_b64 vcc, exec, s[42:43]
	s_cbranch_vccnz .LBB0_2365
	v_pk_mul_f32 v[22:23], v[22:23], v[26:27]
	v_pk_mul_f32 v[24:25], v[24:25], v[40:41]
	v_cvt_pk_bf16_f32 v26, v22, v23
	v_pk_mul_f32 v[22:23], v[42:43], v[48:49]
	v_cvt_pk_bf16_f32 v201, v24, v25
	v_cvt_pk_bf16_f32 v22, v22, v23
	ds_write2_b32 v204, v26, v22 offset1:68
	v_pk_mul_f32 v[22:23], v[86:87], v[90:91]
	v_pk_mul_f32 v[24:25], v[44:45], v[84:85]
	v_cvt_pk_bf16_f32 v26, v22, v23
	v_pk_mul_f32 v[22:23], v[98:99], v[116:117]
	v_cvt_pk_bf16_f32 v199, v24, v25
	v_cvt_pk_bf16_f32 v22, v22, v23
	ds_write2_b32 v204, v26, v22 offset0:136 offset1:204
	v_pk_mul_f32 v[22:23], v[36:37], v[16:17]
	v_pk_mul_f32 v[24:25], v[88:89], v[92:93]
	v_max_f32_e32 v22, 0xda24260, v22
	v_max_f32_e32 v23, 0xda24260, v23
	v_rcp_f32_e32 v26, v22
	v_rcp_f32_e32 v27, v23
	v_cvt_pk_bf16_f32 v202, v24, v25
	v_pk_mul_f32 v[24:25], v[114:115], v[118:119]
	v_pk_mul_f32 v[22:23], v[22:23], v[96:97]
	v_cvt_pk_bf16_f32 v203, v24, v25
	v_pk_mul_f32 v[24:25], v[26:27], v[94:95]
	v_pk_mul_f32 v[26:27], v[34:35], v[16:17]
	v_cvt_pk_bf16_f32 v36, v22, v23
	v_max_f32_e32 v26, 0xda24260, v26
	v_max_f32_e32 v27, 0xda24260, v27
	v_rcp_f32_e32 v34, v26
	v_rcp_f32_e32 v35, v27
	v_pk_mul_f32 v[22:23], v[26:27], v[50:51]
	v_cvt_pk_bf16_f32 v206, v24, v25
	v_cvt_pk_bf16_f32 v22, v22, v23
	ds_write2_b32 v198, v36, v22 offset0:16 offset1:84
	v_pk_mul_f32 v[22:23], v[32:33], v[16:17]
	v_pk_mul_f32 v[24:25], v[34:35], v[46:47]
	v_max_f32_e32 v22, 0xda24260, v22
	v_max_f32_e32 v23, 0xda24260, v23
	v_pk_mul_f32 v[16:17], v[38:39], v[16:17]
	v_cvt_pk_bf16_f32 v207, v24, v25
	v_rcp_f32_e32 v24, v22
	v_rcp_f32_e32 v25, v23
	v_max_f32_e32 v126, 0xda24260, v16
	v_max_f32_e32 v127, 0xda24260, v17
	v_rcp_f32_e32 v124, v126
	v_rcp_f32_e32 v125, v127
	v_pk_mul_f32 v[120:121], v[22:23], v[18:19]
	v_pk_mul_f32 v[122:123], v[24:25], v[20:21]
	ds_write2_b32 v205, v201, v199 offset1:68
	ds_write2_b32 v205, v202, v203 offset0:136 offset1:204
	ds_write2_b32 v197, v206, v207 offset0:16 offset1:84
.LBB0_2365:
	v_cndmask_b32_e64 v17, v29, v31, s[40:41]
	v_cndmask_b32_e64 v16, v28, v30, s[38:39]
	v_pk_mul_f32 v[16:17], v[112:113], v[16:17]
	v_cvt_pk_bf16_f32 v20, v120, v121
	v_cvt_pk_bf16_f32 v19, v16, v17
	v_lshlrev_b32_e32 v16, 16, v196
	v_and_b32_e32 v17, 0xffff0000, v196
	v_pk_mul_f32 v[16:17], v[126:127], v[16:17]
	v_lshlrev_b32_e32 v18, 16, v19
	v_and_b32_e32 v19, 0xffff0000, v19
	v_cvt_pk_bf16_f32 v21, v122, v123
	v_pk_mul_f32 v[18:19], v[124:125], v[18:19]
	v_cvt_pk_bf16_f32 v16, v16, v17
	ds_write2_b32 v198, v20, v16 offset0:152 offset1:220
	v_cvt_pk_bf16_f32 v20, v18, v19
	v_and_b32_e32 v19, 0xffff, v21
	v_lshlrev_b32_e32 v16, 16, v199
	v_lshlrev_b32_e32 v17, 16, v203
	v_lshlrev_b32_e32 v18, 16, v207
	v_lshrrev_b32_e32 v22, 16, v201
	v_lshrrev_b32_e32 v23, 16, v202
	v_lshrrev_b32_e32 v24, 16, v206
	v_lshrrev_b32_e32 v25, 16, v21
	v_and_or_b32 v16, v201, s11, v16
	v_and_or_b32 v17, v202, s11, v17
	v_and_or_b32 v18, v206, s11, v18
	v_lshl_or_b32 v19, v20, 16, v19
	ds_write2_b32 v197, v21, v20 offset0:152 offset1:220
	ds_write_b128 v200, v[16:19] offset:36864
	v_and_or_b32 v16, v199, s9, v22
	v_and_or_b32 v17, v203, s9, v23
	v_and_or_b32 v18, v207, s9, v24
	v_and_or_b32 v19, v20, s9, v25
	ds_write_b128 v200, v[16:19] offset:37024
	v_lshlrev_b32_e32 v16, 4, v102
	v_add_u32_e32 v84, 0, v16
	s_waitcnt lgkmcnt(0)
	s_barrier
	v_add_u32_e32 v16, 0x1e800, v84
	ds_read_b128 v[40:43], v16
	ds_read_b128 v[44:47], v16 offset:64
	ds_read_b128 v[36:39], v16 offset:128
	ds_read_b128 v[32:35], v16 offset:192
	ds_read_b128 v[28:31], v16 offset:256
	ds_read_b128 v[24:27], v16 offset:320
	ds_read_b128 v[20:23], v16 offset:384
	ds_read_b128 v[16:19], v16 offset:448
	s_mov_b64 s[38:39], -1
	s_and_b64 vcc, exec, s[80:81]
	v_add_u32_e32 v85, s73, v183
	v_add_u32_e32 v86, s4, v183
	s_cbranch_vccz .LBB0_2367
	v_mad_u64_u32 v[88:89], s[38:39], v85, s13, v[84:85]
	v_add_u32_e32 v90, s4, v183
	v_mad_u64_u32 v[114:115], s[38:39], v90, s13, v[84:85]
	ds_read_b128 v[208:211], v88 offset:18432
	ds_read_b128 v[212:215], v114
	ds_read_b128 v[216:219], v88 offset:18496
	ds_read_b128 v[220:223], v114 offset:64
	ds_read_b128 v[224:227], v88 offset:18560
	ds_read_b128 v[228:231], v114 offset:128
	ds_read_b128 v[232:235], v88 offset:18624
	ds_read_b128 v[236:239], v114 offset:192
	s_mov_b64 s[38:39], 0
	s_waitcnt lgkmcnt(6)
	v_mfma_f32_16x16x32_bf16 v[48:51], v[208:211], v[212:215], 0
	s_waitcnt lgkmcnt(4)
	v_mfma_f32_16x16x32_bf16 v[48:51], v[216:219], v[220:223], v[48:51]
	s_waitcnt lgkmcnt(2)
	v_mfma_f32_16x16x32_bf16 v[48:51], v[224:227], v[228:231], v[48:51]
	s_waitcnt lgkmcnt(0)
	v_mfma_f32_16x16x32_bf16 v[48:51], v[232:235], v[236:239], v[48:51]

; #define LAS __attribute__((address_space(3)))
; __device__ __forceinline__ unsigned pk2(float lo, float hi) { const f32x2_t v = {lo, hi}; return __builtin_bit_cast(unsigned, __builtin_convertvector(v, bf16x2_t)); }
; #define MFMA16(a, b, c) __builtin_amdgcn_mfma_f32_16x16x32_bf16((a), (b), (c), 0, 0, 0)
; __device__ __forceinline__ void phase_hg2(Frame& F, int j, bool ctx_out, bool dry = false) {
;     ...
;                     const int tg = tt * 16 + l15, sg = st * 16 + q4 * 4;
;                     const float a0 = (sg + 0 <= tg) ? a.x : 0.f, a1 = (sg + 1 <= tg) ? a.y : 0.f, a2 = (sg + 2 <= tg) ? a.z : 0.f, a3 = (sg + 3 <= tg) ? a.w : 0.f;
;                     *(LAS v2u*)(ATT + tg * HTS + sg) = (v2u){pk2(a0, a1), pk2(a2, a3)}; }
;                 f32x4 Oa[4];
; #pragma unroll
;                 for (int tt = 0; tt < 4; ++tt) Oa[tt] = (f32x4){0.f, 0.f, 0.f, 0.f};
; #pragma unroll
;                 for (int ks = 0; ks < 4; ++ks) {
;                     const v4u sb4 = (v4u){pk2(S[2 * ks].x, S[2 * ks].y), pk2(S[2 * ks].z, S[2 * ks].w), pk2(S[2 * ks + 1].x, S[2 * ks + 1].y), pk2(S[2 * ks + 1].z, S[2 * ks + 1].w)};
;                     const hb8 fb = __builtin_bit_cast(hb8, sb4);
; #pragma unroll
;                     for (int tt = 0; tt < 4; ++tt) { const v2u a0 = *(const LAS v2u*)(Qt + (tt * 16 + l15) * HQS + ks * 32 + q4 * 4), a1 = *(const LAS v2u*)(Qt + (tt * 16 + l15) * HQS + ks * 32 + 16 + q4 * 4);
;                         const v4u fa4 = (v4u){a0.x, a0.y, a1.x, a1.y}; Oa[tt] = MFMA16(__builtin_bit_cast(hb8, fa4), fb, Oa[tt]); } }
.LBB0_2373:
	v_cmp_le_i32_e32 vcc, v87, v91
	s_waitcnt lgkmcnt(2)
	v_pk_mul_f32 v[20:21], v[52:53], v[20:21]
	v_mul_lo_u32 v52, v183, s13
	s_nop 1
	v_cndmask_b32_e32 v48, 0, v48, vcc
	v_cmp_lt_i32_e32 vcc, v87, v91
	v_lshlrev_b32_e32 v53, 1, v86
	v_pk_mul_f32 v[44:45], v[72:73], v[44:45]
	v_cndmask_b32_e32 v49, 0, v49, vcc
	v_cmp_le_i32_e32 vcc, v88, v91
	v_cvt_pk_bf16_f32 v48, v48, v49
	v_add3_u32 v72, 0, v52, v53
	v_cndmask_b32_e32 v50, 0, v50, vcc
	v_cmp_le_i32_e32 vcc, v89, v91
	v_pk_mul_f32 v[22:23], v[54:55], v[22:23]
	v_pk_mul_f32 v[46:47], v[74:75], v[46:47]
	v_cndmask_b32_e32 v51, 0, v51, vcc
	v_cvt_pk_bf16_f32 v49, v50, v51
	v_mul_lo_u32 v50, v91, s14
	v_add3_u32 v50, s15, v50, v90
	ds_write_b64 v50, v[48:49]
	ds_read_b64 v[52:53], v72
	ds_read_b64 v[54:55], v72 offset:32
	v_add_u32_e32 v73, 0x1000, v72
	v_add_u32_e32 v74, 0x2000, v72
	v_add_u32_e32 v75, 0x3000, v72
	v_pk_mul_f32 v[34:35], v[66:67], v[34:35]
	v_pk_mul_f32 v[32:33], v[64:65], v[32:33]
	v_pk_mul_f32 v[30:31], v[62:63], v[30:31]
	v_pk_mul_f32 v[28:29], v[60:61], v[28:29]
	v_pk_mul_f32 v[26:27], v[58:59], v[26:27]
	v_pk_mul_f32 v[24:25], v[56:57], v[24:25]
	ds_read_b64 v[56:57], v73 offset:256
	ds_read_b64 v[58:59], v73 offset:288
	ds_read_b64 v[60:61], v74 offset:512
	ds_read_b64 v[62:63], v74 offset:544
	ds_read_b64 v[64:65], v75 offset:768
	ds_read_b64 v[66:67], v75 offset:800
	v_pk_mul_f32 v[38:39], v[70:71], v[38:39]
	v_pk_mul_f32 v[36:37], v[68:69], v[36:37]
	ds_read_b64 v[68:69], v72 offset:64
	ds_read_b64 v[70:71], v72 offset:96
	v_pk_mul_f32 v[42:43], v[78:79], v[42:43]
	v_pk_mul_f32 v[40:41], v[76:77], v[40:41]
	v_cvt_pk_bf16_f32 v49, v42, v43
	v_cvt_pk_bf16_f32 v48, v40, v41
	v_cvt_pk_bf16_f32 v50, v44, v45
	v_cvt_pk_bf16_f32 v51, v46, v47
	s_waitcnt lgkmcnt(12)
	v_pk_mul_f32 v[18:19], v[82:83], v[18:19]
	v_pk_mul_f32 v[16:17], v[80:81], v[16:17]
	s_waitcnt lgkmcnt(8)
	v_mfma_f32_16x16x32_bf16 v[52:55], v[52:55], v[48:51], 0
	v_lshlrev_b32_e32 v85, 3, v102
	v_mul_lo_u32 v76, v183, s14
	v_add_u32_e32 v80, 0xa00, v76
	s_waitcnt lgkmcnt(6)
	v_mfma_f32_16x16x32_bf16 v[56:59], v[56:59], v[48:51], 0
	v_add_u32_e32 v87, 0x1400, v76
	v_add_u32_e32 v88, 0x1e00, v76
	v_add_u32_e32 v99, v84, v76
	s_waitcnt lgkmcnt(4)
	v_mfma_f32_16x16x32_bf16 v[60:63], v[60:63], v[48:51], 0
	v_add_u32_e32 v118, v84, v80
	v_add_u32_e32 v119, v84, v87
	v_add_u32_e32 v120, v84, v88
	s_waitcnt lgkmcnt(2)
	v_mfma_f32_16x16x32_bf16 v[48:51], v[64:67], v[48:51], 0
	v_cvt_pk_bf16_f32 v64, v36, v37
	v_cvt_pk_bf16_f32 v65, v38, v39
	v_cvt_pk_bf16_f32 v66, v32, v33
	v_cvt_pk_bf16_f32 v67, v34, v35
	s_movk_i32 s8, 0x840
	s_and_b64 vcc, exec, s[0:1]
	s_waitcnt lgkmcnt(0)
	v_mfma_f32_16x16x32_bf16 v[52:55], v[68:71], v[64:67], v[52:55]
	ds_read_b64 v[68:69], v73 offset:320
	ds_read_b64 v[70:71], v73 offset:352
	s_waitcnt lgkmcnt(0)
	v_mfma_f32_16x16x32_bf16 v[56:59], v[68:71], v[64:67], v[56:59]
	ds_read_b64 v[68:69], v74 offset:576
	ds_read_b64 v[70:71], v74 offset:608
	s_waitcnt lgkmcnt(0)
	v_mfma_f32_16x16x32_bf16 v[60:63], v[68:71], v[64:67], v[60:63]
	ds_read_b64 v[68:69], v75 offset:832
	ds_read_b64 v[70:71], v75 offset:864
	s_waitcnt lgkmcnt(0)
	v_mfma_f32_16x16x32_bf16 v[48:51], v[68:71], v[64:67], v[48:51]
	ds_read_b64 v[68:69], v72 offset:128
	ds_read_b64 v[70:71], v72 offset:160
	v_cvt_pk_bf16_f32 v64, v28, v29
	v_cvt_pk_bf16_f32 v65, v30, v31
	v_cvt_pk_bf16_f32 v66, v24, v25
	v_cvt_pk_bf16_f32 v67, v26, v27
	s_waitcnt lgkmcnt(0)
	s_nop 0
	v_mfma_f32_16x16x32_bf16 v[52:55], v[68:71], v[64:67], v[52:55]
	ds_read_b64 v[68:69], v73 offset:384
	ds_read_b64 v[70:71], v73 offset:416
	s_waitcnt lgkmcnt(0)
	v_mfma_f32_16x16x32_bf16 v[56:59], v[68:71], v[64:67], v[56:59]
	ds_read_b64 v[68:69], v74 offset:640
	ds_read_b64 v[70:71], v74 offset:672
	s_waitcnt lgkmcnt(0)
	v_mfma_f32_16x16x32_bf16 v[60:63], v[68:71], v[64:67], v[60:63]
	ds_read_b64 v[68:69], v75 offset:896
	ds_read_b64 v[70:71], v75 offset:928
	s_waitcnt lgkmcnt(0)
	v_mfma_f32_16x16x32_bf16 v[48:51], v[68:71], v[64:67], v[48:51]
	ds_read_b64 v[68:69], v72 offset:192
	ds_read_b64 v[70:71], v72 offset:224
	v_cvt_pk_bf16_f32 v64, v20, v21
	v_cvt_pk_bf16_f32 v65, v22, v23
	v_cvt_pk_bf16_f32 v66, v16, v17
	v_cvt_pk_bf16_f32 v67, v18, v19
	s_waitcnt lgkmcnt(0)
	s_nop 0
	v_mfma_f32_16x16x32_bf16 v[52:55], v[68:71], v[64:67], v[52:55]
	ds_read_b64 v[68:69], v73 offset:448
	ds_read_b64 v[70:71], v73 offset:480
	s_waitcnt lgkmcnt(0)
	v_mfma_f32_16x16x32_bf16 v[56:59], v[68:71], v[64:67], v[56:59]
	ds_read_b64 v[68:69], v74 offset:704
	ds_read_b64 v[70:71], v74 offset:736
	s_waitcnt lgkmcnt(0)
	v_mfma_f32_16x16x32_bf16 v[60:63], v[68:71], v[64:67], v[60:63]
	ds_read_b64 v[68:69], v75 offset:960
	ds_read_b64 v[70:71], v75 offset:992
	s_waitcnt lgkmcnt(0)
	s_barrier
; #define LAS __attribute__((address_space(3)))
; #define LDS_BARRIER() do { asm volatile("s_waitcnt lgkmcnt(0)" ::: "memory"); __builtin_amdgcn_s_barrier(); asm volatile("" ::: "memory"); } while (0)
; #define MFMA16(a, b, c) __builtin_amdgcn_mfma_f32_16x16x32_bf16((a), (b), (c), 0, 0, 0)
; __device__ __forceinline__ void phase_hg2(Frame& F, int j, bool ctx_out, bool dry = false) {
;     ...
; #pragma unroll
;                 for (int ss = 0; ss < 2; ++ss) { const hb8 fb = *(const LAS hb8*)(VT + (vb * 16 + l15) * HTS + ss * 32 + q4 * 8);
; #pragma unroll
;                     for (int tt = 0; tt < 4; ++tt) { const hb8 fa = *(const LAS hb8*)(ATT + (tt * 16 + l15) * HTS + ss * 32 + q4 * 8); Oa[tt] = MFMA16(fa, fb, Oa[tt]); }
; #pragma unroll
;                     for (int kt = 0; kt < 8; ++kt) { const hb8 fa = *(const LAS hb8*)(KtT + (kt * 16 + l15) * HTS + ss * 32 + q4 * 8); S[kt] = MFMA16(fa, fb, S[kt]); } }
; #pragma unroll
;                 for (int kt = 0; kt < 8; ++kt) { const f32x4 e4 = *(const LAS f32x4*)(eend + kt * 16 + q4 * 4); S[kt] = S[kt] * e4; }
; #pragma unroll
;                 for (int tt = 0; tt < 4; ++tt) {
; #pragma unroll
;                     for (int i = 0; i < 4; ++i) O32[(tt * 16 + q4 * 4 + i) * HOS + vb * 16 + l15] = Oa[tt][i]; }
;                 LDS_BARRIER();
;                 {
;                     f32x4 o[4];
; #pragma unroll
;                     for (int u = 0; u < 4; ++u) o[u] = *(const LAS f32x4*)(O32 + rto * HOS + g8o * 16 + u * 4);
	s_waitcnt lgkmcnt(0)
	v_mfma_f32_16x16x32_bf16 v[48:51], v[68:71], v[64:67], v[48:51]
	v_add_u32_e32 v64, s34, v183
	v_lshlrev_b32_e32 v65, 1, v85
	v_mul_lo_u32 v64, v64, s14
	v_add_u32_e32 v72, s15, v65
	v_add3_u32 v85, 0, v64, v65
	v_add_u32_e32 v86, v72, v76
	v_add_u32_e32 v90, v72, v80
	v_add_u32_e32 v94, v72, v87
	v_add_u32_e32 v98, v72, v88
	ds_read_b128 v[240:243], v85 offset:57344
	ds_read_b128 v[208:211], v86
	ds_read_b128 v[212:215], v90
	ds_read_b128 v[216:219], v94
	ds_read_b128 v[220:223], v98
	ds_read_b128 v[224:227], v99 offset:36864
	ds_read_b128 v[228:231], v118 offset:36864
	ds_read_b128 v[232:235], v119 offset:36864
	ds_read_b128 v[236:239], v120 offset:36864
	s_waitcnt lgkmcnt(7)
	v_mfma_f32_16x16x32_bf16 v[68:71], v[208:211], v[240:243], v[52:55]
	ds_read_b128 v[208:211], v99 offset:47104
	s_waitcnt lgkmcnt(7)
	v_mfma_f32_16x16x32_bf16 v[56:59], v[212:215], v[240:243], v[56:59]
	ds_read_b128 v[212:215], v99 offset:49664
	s_waitcnt lgkmcnt(7)
	v_mfma_f32_16x16x32_bf16 v[60:63], v[216:219], v[240:243], v[60:63]
	ds_read_b128 v[216:219], v99 offset:52224
	s_waitcnt lgkmcnt(7)
	v_mfma_f32_16x16x32_bf16 v[72:75], v[220:223], v[240:243], v[48:51]
	ds_read_b128 v[220:223], v99 offset:54784
	s_waitcnt lgkmcnt(7)
	v_mfma_f32_16x16x32_bf16 v[76:79], v[224:227], v[240:243], v[40:43]
	ds_read_b128 v[244:247], v85 offset:57408
	ds_read_b128 v[224:227], v86 offset:64
	s_waitcnt lgkmcnt(8)
	v_mfma_f32_16x16x32_bf16 v[80:83], v[228:231], v[240:243], v[44:47]
	ds_read_b128 v[228:231], v120 offset:36928
	s_waitcnt lgkmcnt(8)
	v_mfma_f32_16x16x32_bf16 v[52:55], v[232:235], v[240:243], v[36:39]
	ds_read_b128 v[232:235], v90 offset:64
	s_waitcnt lgkmcnt(8)
	v_mfma_f32_16x16x32_bf16 v[48:51], v[236:239], v[240:243], v[32:35]
	ds_read_b128 v[236:239], v99 offset:47168
	s_waitcnt lgkmcnt(8)
	v_mfma_f32_16x16x32_bf16 v[32:35], v[208:211], v[240:243], v[28:31]
	ds_read_b128 v[208:211], v94 offset:64
	s_waitcnt lgkmcnt(8)
	v_mfma_f32_16x16x32_bf16 v[36:39], v[212:215], v[240:243], v[24:27]
	ds_read_b128 v[212:215], v99 offset:49728
	s_waitcnt lgkmcnt(8)
	v_mfma_f32_16x16x32_bf16 v[40:43], v[216:219], v[240:243], v[20:23]
	ds_read_b128 v[216:219], v98 offset:64
	s_waitcnt lgkmcnt(8)
	v_mfma_f32_16x16x32_bf16 v[44:47], v[220:223], v[240:243], v[16:19]
	ds_read_b128 v[220:223], v99 offset:52288
	s_waitcnt lgkmcnt(7)
	v_mfma_f32_16x16x32_bf16 v[86:89], v[224:227], v[244:247], v[68:71]
	ds_read_b128 v[224:227], v118 offset:36928
	s_waitcnt lgkmcnt(7)
	v_mfma_f32_16x16x32_bf16 v[28:31], v[228:231], v[244:247], v[48:51]
	ds_read_b128 v[228:231], v99 offset:54848
	s_waitcnt lgkmcnt(7)
	v_mfma_f32_16x16x32_bf16 v[90:93], v[232:235], v[244:247], v[56:59]
	ds_read_b128 v[232:235], v99 offset:36928
	s_waitcnt lgkmcnt(7)
	v_mfma_f32_16x16x32_bf16 v[32:35], v[236:239], v[244:247], v[32:35]
	ds_read_b128 v[236:239], v119 offset:36928
	s_waitcnt lgkmcnt(7)
	v_mfma_f32_16x16x32_bf16 v[94:97], v[208:211], v[244:247], v[60:63]
	s_waitcnt lgkmcnt(6)
	v_mfma_f32_16x16x32_bf16 v[36:39], v[212:215], v[244:247], v[36:39]
	s_waitcnt lgkmcnt(5)
	v_mfma_f32_16x16x32_bf16 v[114:117], v[216:219], v[244:247], v[72:75]
	s_waitcnt lgkmcnt(4)
	v_mfma_f32_16x16x32_bf16 v[40:43], v[220:223], v[244:247], v[40:43]
	s_waitcnt lgkmcnt(3)
	v_mfma_f32_16x16x32_bf16 v[20:23], v[224:227], v[244:247], v[80:83]
	s_waitcnt lgkmcnt(2)
	v_mfma_f32_16x16x32_bf16 v[44:47], v[228:231], v[244:247], v[44:47]
	s_waitcnt lgkmcnt(1)
	v_mfma_f32_16x16x32_bf16 v[16:19], v[232:235], v[244:247], v[76:79]
	s_waitcnt lgkmcnt(0)
	v_mfma_f32_16x16x32_bf16 v[24:27], v[236:239], v[244:247], v[52:55]
	v_lshlrev_b32_e32 v80, 2, v183
	v_mul_lo_u32 v81, v102, s8
	v_add3_u32 v80, s72, v80, v81
	v_add_u32_e32 v48, 0x1ea00, v84
	v_add_u32_e32 v81, 0x400, v80
	s_movk_i32 s8, 0x210
	s_nop 1
	ds_read_b128 v[76:79], v48
	ds_read_b128 v[72:75], v48 offset:64
	ds_read_b128 v[68:71], v48 offset:128
	ds_read_b128 v[64:67], v48 offset:192
	ds_read_b128 v[60:63], v48 offset:256
	ds_read_b128 v[56:59], v48 offset:320
	ds_read_b128 v[52:55], v48 offset:384
	ds_read_b128 v[48:51], v48 offset:448
	ds_write2_b32 v81, v88, v89 offset0:8 offset1:140
	v_add_u32_e32 v81, 0x2000, v80
	ds_write2_b32 v81, v90, v91 offset0:64 offset1:196
	v_add_u32_e32 v81, 0x2400, v80
	ds_write2_b32 v81, v92, v93 offset0:72 offset1:204
	v_add_u32_e32 v81, 0x4200, v80
	ds_write2_b32 v81, v94, v95 offset1:132
	v_add_u32_e32 v81, 0x4600, v80
	ds_write2_b32 v80, v86, v87 offset1:132
	ds_write2_b32 v81, v96, v97 offset0:8 offset1:140
	v_add_u32_e32 v81, 0x6200, v80
	v_add_u32_e32 v80, 0x6600, v80
	ds_write2_b32 v81, v114, v115 offset0:64 offset1:196
	ds_write2_b32 v80, v116, v117 offset0:72 offset1:204
	v_mul_lo_u32 v80, v195, s8
	v_lshlrev_b32_e32 v81, 2, v194
	s_waitcnt lgkmcnt(0)
	s_barrier
	v_add3_u32 v80, 0, v80, v81
	ds_read_b128 v[92:95], v80
	ds_read_b128 v[88:91], v80 offset:16
	ds_read_b128 v[84:87], v80 offset:32
	ds_read_b128 v[80:83], v80 offset:48
	s_cbranch_vccz .LBB0_2378
; #define GAS __attribute__((address_space(1)))
; #define LAS __attribute__((address_space(3)))
; __device__ __forceinline__ unsigned pk2(float lo, float hi) { const f32x2_t v = {lo, hi}; return __builtin_bit_cast(unsigned, __builtin_convertvector(v, bf16x2_t)); }
; __device__ __forceinline__ float sum8(float x) { x += dppf<0xB1>(x); x += dppf<0x4E>(x); x += dppf<0x141>(x); return x; }
; __device__ __forceinline__ void phase_hg2(Frame& F, int j, bool ctx_out, bool dry = false) {
;     ...
;                     } else if (do_out) {
;                         float ss = 0.f;
; #pragma unroll
;                         for (int u2 = 0; u2 < 2; ++u2) { const v4u f = pf[u2];
;                             o[2 * u2] = o[2 * u2] + (f32x4){bflo(f.x), bfhi(f.x), bflo(f.y), bfhi(f.y)}; o[2 * u2 + 1] = o[2 * u2 + 1] + (f32x4){bflo(f.z), bfhi(f.z), bflo(f.w), bfhi(f.w)}; }
; #pragma unroll
;                         for (int u = 0; u < 4; ++u) ss += (o[u].x * o[u].x + o[u].y * o[u].y) + (o[u].z * o[u].z + o[u].w * o[u].w);
;                         ss = sum8(ss);
;                         const float r = __builtin_amdgcn_rsqf(ss * (1.f / 128.f) + RMS_EPS);
;                         GAS v4u* gp = (GAS v4u*)((GAS char*)(P + 4 * DM + h * 128) + ((unsigned)rrow * HG_N + g8o * 16) * 2u);
; #pragma unroll
;                         for (int u2 = 0; u2 < 2; ++u2) { const v4u rg = pg[u2]; const f32x4 oa = o[2 * u2], ob2 = o[2 * u2 + 1]; const f32x4 nga = *(const LAS f32x4*)(s_ng + g8o * 16 + u2 * 8), ngb = *(const LAS f32x4*)(s_ng + g8o * 16 + u2 * 8 + 4); const float ngp[8] = {nga.x, nga.y, nga.z, nga.w, ngb.x, ngb.y, ngb.z, ngb.w};
;                             const float y0 = oa.x * r * ngp[0] * bflo(rg.x), y1 = oa.y * r * ngp[1] * bfhi(rg.x), y2 = oa.z * r * ngp[2] * bflo(rg.y), y3 = oa.w * r * ngp[3] * bfhi(rg.y);
;                             const float y4 = ob2.x * r * ngp[4] * bflo(rg.z), y5 = ob2.y * r * ngp[5] * bfhi(rg.z), y6 = ob2.z * r * ngp[6] * bflo(rg.w), y7 = ob2.w * r * ngp[7] * bfhi(rg.w);
;                             gp[u2] = (v4u){pk2(y0, y1), pk2(y2, y3), pk2(y4, y5), pk2(y6, y7)}; }
	s_mov_b64 s[38:39], 0
	s_and_b64 vcc, exec, s[36:37]
	s_mov_b64 s[36:37], 0
	s_cbranch_vccz .LBB0_2376
	s_waitcnt vmcnt(26)
	v_lshlrev_b32_e32 v96, 16, v12
	v_and_b32_e32 v97, 0xffff0000, v12
	v_lshlrev_b32_e32 v12, 16, v13
	v_and_b32_e32 v13, 0xffff0000, v13
	s_waitcnt lgkmcnt(3)
	v_pk_add_f32 v[122:123], v[94:95], v[12:13]
	v_lshlrev_b32_e32 v12, 16, v14
	v_and_b32_e32 v13, 0xffff0000, v14
	s_waitcnt lgkmcnt(2)
	v_pk_add_f32 v[124:125], v[88:89], v[12:13]
	v_lshlrev_b32_e32 v12, 16, v8
	v_and_b32_e32 v13, 0xffff0000, v8
	v_lshlrev_b32_e32 v8, 16, v9
	v_and_b32_e32 v9, 0xffff0000, v9
	v_pk_add_f32 v[120:121], v[92:93], v[96:97]
	s_waitcnt lgkmcnt(1)
	v_pk_add_f32 v[196:197], v[86:87], v[8:9]
	v_lshlrev_b32_e32 v8, 16, v10
	v_and_b32_e32 v9, 0xffff0000, v10
	v_lshlrev_b32_e32 v10, 16, v11
	v_and_b32_e32 v11, 0xffff0000, v11
	v_lshlrev_b32_e32 v14, 16, v15
	v_and_b32_e32 v15, 0xffff0000, v15
	s_waitcnt lgkmcnt(0)
	v_pk_add_f32 v[200:201], v[82:83], v[10:11]
	v_pk_add_f32 v[202:203], v[80:81], v[8:9]
	v_pk_mul_f32 v[8:9], v[122:123], v[122:123]
	v_pk_mul_f32 v[10:11], v[120:121], v[120:121]
	v_pk_add_f32 v[126:127], v[90:91], v[14:15]
	v_pk_add_f32 v[198:199], v[84:85], v[12:13]
	v_pk_mov_b32 v[12:13], v[10:11], v[8:9] op_sel:[1,0]
	v_mov_b32_e32 v11, v9
	v_pk_add_f32 v[8:9], v[12:13], v[10:11]
	v_pk_mul_f32 v[10:11], v[126:127], v[126:127]
	v_pk_mul_f32 v[12:13], v[124:125], v[124:125]
	v_pk_add_f32 v[8:9], v[8:9], v[8:9] op_sel:[0,1] op_sel_hi:[1,0]
	v_pk_mov_b32 v[14:15], v[12:13], v[10:11] op_sel:[1,0]
	v_mov_b32_e32 v13, v11
	v_pk_add_f32 v[10:11], v[14:15], v[12:13]
	v_mul_f32_e32 v12, v202, v202
	v_mul_f32_e32 v13, v203, v203
	v_pk_add_f32 v[10:11], v[10:11], v[10:11] op_sel:[0,1] op_sel_hi:[1,0]
	v_mov_b32_e32 v9, v12
	v_mov_b32_e32 v11, v13
	v_pk_add_f32 v[8:9], v[8:9], v[10:11]
	v_mul_f32_e32 v10, v199, v199
	v_mul_f32_e32 v12, v197, v197
	v_mul_f32_e32 v14, v200, v200
	v_mul_f32_e32 v15, v201, v201
	v_pk_fma_f32 v[10:11], v[198:199], v[198:199], v[10:11] op_sel_hi:[1,1,0]
	v_pk_fma_f32 v[12:13], v[196:197], v[196:197], v[12:13] op_sel_hi:[1,1,0]
	v_mov_b32_e32 v11, v14
	v_mov_b32_e32 v13, v15
	v_pk_add_f32 v[10:11], v[10:11], v[12:13]
	s_movk_i32 s8, 0x2800
	v_pk_add_f32 v[8:9], v[8:9], v[10:11]
	s_mov_b64 s[36:37], -1
	v_add_f32_e32 v8, v8, v9
	s_nop 1
	v_add_f32_dpp v8, v8, v8 quad_perm:[1,0,3,2] row_mask:0xf bank_mask:0xf bound_ctrl:1
	s_nop 1
	v_add_f32_dpp v8, v8, v8 quad_perm:[2,3,0,1] row_mask:0xf bank_mask:0xf bound_ctrl:1
	s_nop 1
	v_add_f32_dpp v8, v8, v8 row_half_mirror row_mask:0xf bank_mask:0xf bound_ctrl:1
	v_fmamk_f32 v8, v8, 0x3c000000, v165
	v_rsq_f32_e32 v204, v8
	v_mul_lo_u32 v8, v188, s8
	v_add_lshl_u32 v102, v8, v194, 1
	v_lshl_add_u32 v8, v194, 2, 0
	v_add_u32_e32 v116, 0x20000, v8
	ds_read_b128 v[8:11], v116
	ds_read_b128 v[12:15], v116 offset:16
	ds_read_b128 v[96:99], v116 offset:32
	ds_read_b128 v[116:119], v116 offset:48
	v_pk_mul_f32 v[120:121], v[120:121], v[204:205] op_sel_hi:[1,0]
	v_lshl_add_u64 v[114:115], s[90:91], 0, v[102:103]
	s_waitcnt lgkmcnt(3)
	v_pk_mul_f32 v[8:9], v[8:9], v[120:121]
	s_waitcnt vmcnt(24)
	v_lshlrev_b32_e32 v120, 16, v4
	v_and_b32_e32 v121, 0xffff0000, v4
	v_pk_mul_f32 v[8:9], v[8:9], v[120:121]
	v_pk_mul_f32 v[120:121], v[122:123], v[204:205] op_sel_hi:[1,0]
	v_lshlrev_b32_e32 v4, 16, v5
	v_pk_mul_f32 v[10:11], v[10:11], v[120:121]
	v_and_b32_e32 v5, 0xffff0000, v5
	v_pk_mul_f32 v[10:11], v[10:11], v[4:5]
	v_pk_mul_f32 v[4:5], v[124:125], v[204:205] op_sel_hi:[1,0]
	s_waitcnt lgkmcnt(2)
	v_pk_mul_f32 v[4:5], v[12:13], v[4:5]
	v_lshlrev_b32_e32 v12, 16, v6
	v_and_b32_e32 v13, 0xffff0000, v6
	v_pk_mul_f32 v[12:13], v[4:5], v[12:13]
	v_pk_mul_f32 v[4:5], v[126:127], v[204:205] op_sel_hi:[1,0]
	v_lshlrev_b32_e32 v6, 16, v7
	v_pk_mul_f32 v[4:5], v[14:15], v[4:5]
	v_and_b32_e32 v7, 0xffff0000, v7
	v_pk_mul_f32 v[14:15], v[4:5], v[6:7]
	v_cvt_pk_bf16_f32 v4, v8, v9
	v_cvt_pk_bf16_f32 v5, v10, v11
	v_cvt_pk_bf16_f32 v6, v12, v13
	v_cvt_pk_bf16_f32 v7, v14, v15
	global_store_dwordx4 v102, v[4:7], s[90:91]
	v_lshlrev_b32_e32 v8, 16, v2
	v_and_b32_e32 v9, 0xffff0000, v2
	v_pk_mul_f32 v[4:5], v[198:199], v[204:205] op_sel_hi:[1,0]
	v_lshlrev_b32_e32 v6, 16, v0
	s_waitcnt lgkmcnt(1)
	v_pk_mul_f32 v[4:5], v[96:97], v[4:5]
	v_and_b32_e32 v7, 0xffff0000, v0
	v_pk_mul_f32 v[4:5], v[4:5], v[6:7]
	v_pk_mul_f32 v[6:7], v[196:197], v[204:205] op_sel_hi:[1,0]
	v_lshlrev_b32_e32 v0, 16, v1
	v_pk_mul_f32 v[6:7], v[98:99], v[6:7]
	v_and_b32_e32 v1, 0xffff0000, v1
	v_pk_mul_f32 v[0:1], v[6:7], v[0:1]
	v_pk_mul_f32 v[6:7], v[202:203], v[204:205] op_sel_hi:[1,0]
	v_lshlrev_b32_e32 v2, 16, v3
	s_waitcnt lgkmcnt(0)
	v_pk_mul_f32 v[6:7], v[6:7], v[116:117]
	v_and_b32_e32 v3, 0xffff0000, v3
	v_pk_mul_f32 v[6:7], v[6:7], v[8:9]
	v_pk_mul_f32 v[8:9], v[200:201], v[204:205] op_sel_hi:[1,0]
	v_cvt_pk_bf16_f32 v96, v4, v5
	v_pk_mul_f32 v[8:9], v[8:9], v[118:119]
	v_cvt_pk_bf16_f32 v97, v0, v1
	v_pk_mul_f32 v[116:117], v[8:9], v[2:3]
	v_cvt_pk_bf16_f32 v98, v6, v7
	s_and_b64 vcc, exec, s[38:39]
	s_cbranch_vccz .LBB0_2379
	s_branch .LBB0_2377
